# all 32-MFMA runs of the GEMM K loops padded (s_nop 0) to start at 8-byte aligned addresses, on top of v089
# baseline (speedup 1.0000x reference)
.LBB0_341:
	ds_read_b128 v[128:131], v225
	ds_read_b128 v[132:135], v225 offset:1024
	ds_read_b128 v[136:139], v225 offset:2048
	ds_read_b128 v[140:143], v225 offset:3072
	ds_read_b128 v[144:147], v226
	ds_read_b128 v[148:151], v226 offset:1024
	ds_read_b128 v[152:155], v226 offset:2048
	ds_read_b128 v[156:159], v226 offset:3072
	s_add_u32 s26, s48, 0xfffc0080
	s_addc_u32 s27, s49, -1
	s_cmp_eq_u32 vcc_lo, 12
	s_cselect_b32 s53, s41, s27
	s_cselect_b32 s52, s47, s26
	s_cselect_b32 s51, s39, s97
	s_cselect_b32 s50, s93, s96
	v_lshl_add_u64 v[214:215], s[48:49], 0, v[204:205]
	s_add_i32 m0, s56, 0xc000
	ds_read_b128 v[160:163], v227
	ds_read_b128 v[164:167], v227 offset:1024
	ds_read_b128 v[168:171], v227 offset:2048
	ds_read_b128 v[172:175], v227 offset:3072
	ds_read_b128 v[176:179], v227 offset:4096
	ds_read_b128 v[180:183], v227 offset:5120
	ds_read_b128 v[184:187], v227 offset:6144
	ds_read_b128 v[188:191], v227 offset:7168
	global_load_lds_dwordx4 v[214:215], off
	v_lshl_add_u64 v[214:215], s[48:49], 0, v[206:207]
	s_add_i32 m0, s56, 0xe000
	s_nop 0
	global_load_lds_dwordx4 v[214:215], off
	s_waitcnt vmcnt(8)
	s_waitcnt lgkmcnt(0)
	s_barrier
	s_setprio 1
	s_waitcnt lgkmcnt(0)
	v_mfma_f32_16x16x32_bf16 v[124:127], v[128:131], v[160:163], v[124:127]
	v_mfma_f32_16x16x32_bf16 v[120:123], v[136:139], v[160:163], v[120:123]
	v_mfma_f32_16x16x32_bf16 v[108:111], v[128:131], v[168:171], v[108:111]
	v_mfma_f32_16x16x32_bf16 v[104:107], v[136:139], v[168:171], v[104:107]
	v_mfma_f32_16x16x32_bf16 v[92:95], v[128:131], v[176:179], v[92:95]
	v_mfma_f32_16x16x32_bf16 v[88:91], v[136:139], v[176:179], v[88:91]
	v_mfma_f32_16x16x32_bf16 v[76:79], v[128:131], v[184:187], v[76:79]
	v_mfma_f32_16x16x32_bf16 v[72:75], v[136:139], v[184:187], v[72:75]
	v_mfma_f32_16x16x32_bf16 v[124:127], v[132:135], v[164:167], v[124:127]
	v_mfma_f32_16x16x32_bf16 v[120:123], v[140:143], v[164:167], v[120:123]
	v_mfma_f32_16x16x32_bf16 v[108:111], v[132:135], v[172:175], v[108:111]
	v_mfma_f32_16x16x32_bf16 v[104:107], v[140:143], v[172:175], v[104:107]
	v_mfma_f32_16x16x32_bf16 v[92:95], v[132:135], v[180:183], v[92:95]
	v_mfma_f32_16x16x32_bf16 v[88:91], v[140:143], v[180:183], v[88:91]
	v_mfma_f32_16x16x32_bf16 v[76:79], v[132:135], v[188:191], v[76:79]
	v_mfma_f32_16x16x32_bf16 v[72:75], v[140:143], v[188:191], v[72:75]
	s_setprio 0
	s_setprio 1
	v_mfma_f32_16x16x32_bf16 v[116:119], v[144:147], v[160:163], v[116:119]
	v_mfma_f32_16x16x32_bf16 v[112:115], v[152:155], v[160:163], v[112:115]
	v_mfma_f32_16x16x32_bf16 v[100:103], v[144:147], v[168:171], v[100:103]
	v_mfma_f32_16x16x32_bf16 v[96:99], v[152:155], v[168:171], v[96:99]
	v_mfma_f32_16x16x32_bf16 v[84:87], v[144:147], v[176:179], v[84:87]
	v_mfma_f32_16x16x32_bf16 v[80:83], v[152:155], v[176:179], v[80:83]
	v_mfma_f32_16x16x32_bf16 v[68:71], v[144:147], v[184:187], v[68:71]
	v_mfma_f32_16x16x32_bf16 v[64:67], v[152:155], v[184:187], v[64:67]
	v_mfma_f32_16x16x32_bf16 v[116:119], v[148:151], v[164:167], v[116:119]
	v_mfma_f32_16x16x32_bf16 v[112:115], v[156:159], v[164:167], v[112:115]
	v_mfma_f32_16x16x32_bf16 v[100:103], v[148:151], v[172:175], v[100:103]
	v_mfma_f32_16x16x32_bf16 v[96:99], v[156:159], v[172:175], v[96:99]
	v_mfma_f32_16x16x32_bf16 v[84:87], v[148:151], v[180:183], v[84:87]
	v_mfma_f32_16x16x32_bf16 v[80:83], v[156:159], v[180:183], v[80:83]
	v_mfma_f32_16x16x32_bf16 v[68:71], v[148:151], v[188:191], v[68:71]
	v_mfma_f32_16x16x32_bf16 v[64:67], v[156:159], v[188:191], v[64:67]
	s_setprio 0
	s_barrier
	s_add_i32 s26, s68, s3
	v_lshl_add_u64 v[214:215], s[50:51], 0, v[194:195]
	s_mov_b32 m0, s26
	ds_read_b128 v[160:163], v227 offset:16384
	ds_read_b128 v[164:167], v227 offset:17408
	ds_read_b128 v[168:171], v227 offset:18432
	ds_read_b128 v[172:175], v227 offset:19456
	ds_read_b128 v[176:179], v227 offset:20480
	ds_read_b128 v[180:183], v227 offset:21504
	ds_read_b128 v[184:187], v227 offset:22528
	ds_read_b128 v[188:191], v227 offset:23552
	global_load_lds_dwordx4 v[214:215], off
	s_add_i32 m0, s26, 0x2000
	s_add_u32 s26, s50, 0x40000
	v_lshl_add_u64 v[216:217], s[50:51], 0, v[198:199]
	s_addc_u32 s27, s51, 0
	s_add_i32 s72, s69, s3
	global_load_lds_dwordx4 v[216:217], off
	v_lshl_add_u64 v[218:219], s[26:27], 0, v[194:195]
	s_mov_b32 m0, s72
	v_lshl_add_u64 v[228:229], s[52:53], 0, v[196:197]
	global_load_lds_dwordx4 v[218:219], off
	v_lshl_add_u64 v[218:219], s[26:27], 0, v[198:199]
	s_add_i32 m0, s72, 0x2000
	s_nop 0
	global_load_lds_dwordx4 v[218:219], off
	v_lshl_add_u64 v[218:219], s[52:53], 0, v[192:193]
	s_mov_b32 m0, s56
	s_nop 0
	global_load_lds_dwordx4 v[218:219], off
	s_mov_b32 m0, s57
	s_nop 0
	global_load_lds_dwordx4 v[228:229], off
	s_waitcnt vmcnt(8)
	s_waitcnt lgkmcnt(0)
	s_barrier
	s_setprio 1
	s_waitcnt lgkmcnt(0)
	s_nop 0
	v_mfma_f32_16x16x32_bf16 v[60:63], v[128:131], v[160:163], v[60:63]
	v_mfma_f32_16x16x32_bf16 v[56:59], v[136:139], v[160:163], v[56:59]
	v_mfma_f32_16x16x32_bf16 v[48:51], v[128:131], v[168:171], v[48:51]
	v_mfma_f32_16x16x32_bf16 v[40:43], v[136:139], v[168:171], v[40:43]
	v_mfma_f32_16x16x32_bf16 v[32:35], v[128:131], v[176:179], v[32:35]
	v_mfma_f32_16x16x32_bf16 v[24:27], v[136:139], v[176:179], v[24:27]
	v_mfma_f32_16x16x32_bf16 v[16:19], v[128:131], v[184:187], v[16:19]
	v_mfma_f32_16x16x32_bf16 v[8:11], v[136:139], v[184:187], v[8:11]
	v_mfma_f32_16x16x32_bf16 v[60:63], v[132:135], v[164:167], v[60:63]
	v_mfma_f32_16x16x32_bf16 v[56:59], v[140:143], v[164:167], v[56:59]
	v_mfma_f32_16x16x32_bf16 v[48:51], v[132:135], v[172:175], v[48:51]
	v_mfma_f32_16x16x32_bf16 v[40:43], v[140:143], v[172:175], v[40:43]
	v_mfma_f32_16x16x32_bf16 v[32:35], v[132:135], v[180:183], v[32:35]
	v_mfma_f32_16x16x32_bf16 v[24:27], v[140:143], v[180:183], v[24:27]
	v_mfma_f32_16x16x32_bf16 v[16:19], v[132:135], v[188:191], v[16:19]
	v_mfma_f32_16x16x32_bf16 v[8:11], v[140:143], v[188:191], v[8:11]
	s_setprio 0
	s_setprio 1
	v_mfma_f32_16x16x32_bf16 v[52:55], v[144:147], v[160:163], v[52:55]
	v_mfma_f32_16x16x32_bf16 v[44:47], v[152:155], v[160:163], v[44:47]
	v_mfma_f32_16x16x32_bf16 v[36:39], v[144:147], v[168:171], v[36:39]
	v_mfma_f32_16x16x32_bf16 v[28:31], v[152:155], v[168:171], v[28:31]
	v_mfma_f32_16x16x32_bf16 v[20:23], v[144:147], v[176:179], v[20:23]
	v_mfma_f32_16x16x32_bf16 v[12:15], v[152:155], v[176:179], v[12:15]
	v_mfma_f32_16x16x32_bf16 v[4:7], v[144:147], v[184:187], v[4:7]
	v_mfma_f32_16x16x32_bf16 v[0:3], v[152:155], v[184:187], v[0:3]
	v_mfma_f32_16x16x32_bf16 v[52:55], v[148:151], v[164:167], v[52:55]
	v_mfma_f32_16x16x32_bf16 v[44:47], v[156:159], v[164:167], v[44:47]
	v_mfma_f32_16x16x32_bf16 v[36:39], v[148:151], v[172:175], v[36:39]
	v_mfma_f32_16x16x32_bf16 v[28:31], v[156:159], v[172:175], v[28:31]
	v_mfma_f32_16x16x32_bf16 v[20:23], v[148:151], v[180:183], v[20:23]
	v_mfma_f32_16x16x32_bf16 v[12:15], v[156:159], v[180:183], v[12:15]
	v_mfma_f32_16x16x32_bf16 v[4:7], v[148:151], v[188:191], v[4:7]
	v_mfma_f32_16x16x32_bf16 v[0:3], v[156:159], v[188:191], v[0:3]
	s_setprio 0
	s_barrier
	s_add_i32 s72, 0, 0x18000
	s_add_i32 s73, 0, 0x1c000
	v_add_u32_e32 v140, s72, v223
	v_add_u32_e32 v156, s73, v223
	ds_read_b128 v[128:131], v140
	ds_read_b128 v[132:135], v140 offset:1024
	ds_read_b128 v[136:139], v140 offset:2048
	ds_read_b128 v[140:143], v140 offset:3072
	ds_read_b128 v[144:147], v156
	ds_read_b128 v[148:151], v156 offset:1024
	ds_read_b128 v[152:155], v156 offset:2048
	ds_read_b128 v[156:159], v156 offset:3072
	s_add_u32 s26, s52, 0x40000
	s_addc_u32 s27, s53, 0
	s_mov_b32 m0, s58
	v_lshl_add_u64 v[230:231], s[26:27], 0, v[192:193]
	ds_read_b128 v[160:163], v227 offset:32768
	ds_read_b128 v[164:167], v227 offset:33792
	ds_read_b128 v[168:171], v227 offset:34816
	ds_read_b128 v[172:175], v227 offset:35840
	ds_read_b128 v[176:179], v227 offset:36864
	ds_read_b128 v[180:183], v227 offset:37888
	ds_read_b128 v[184:187], v227 offset:38912
	ds_read_b128 v[188:191], v227 offset:39936
	global_load_lds_dwordx4 v[230:231], off
	v_lshl_add_u64 v[230:231], s[26:27], 0, v[196:197]
	s_mov_b32 m0, s59
	s_nop 0
	global_load_lds_dwordx4 v[230:231], off
	s_waitcnt vmcnt(8)
	s_waitcnt lgkmcnt(0)
	s_barrier
	s_setprio 1
	s_waitcnt lgkmcnt(0)
	s_nop 0
	v_mfma_f32_16x16x32_bf16 v[124:127], v[128:131], v[160:163], v[124:127]
	v_mfma_f32_16x16x32_bf16 v[120:123], v[136:139], v[160:163], v[120:123]
	v_mfma_f32_16x16x32_bf16 v[108:111], v[128:131], v[168:171], v[108:111]
	v_mfma_f32_16x16x32_bf16 v[104:107], v[136:139], v[168:171], v[104:107]
	v_mfma_f32_16x16x32_bf16 v[92:95], v[128:131], v[176:179], v[92:95]
	v_mfma_f32_16x16x32_bf16 v[88:91], v[136:139], v[176:179], v[88:91]
	v_mfma_f32_16x16x32_bf16 v[76:79], v[128:131], v[184:187], v[76:79]
	v_mfma_f32_16x16x32_bf16 v[72:75], v[136:139], v[184:187], v[72:75]
	v_mfma_f32_16x16x32_bf16 v[124:127], v[132:135], v[164:167], v[124:127]
	v_mfma_f32_16x16x32_bf16 v[120:123], v[140:143], v[164:167], v[120:123]
	v_mfma_f32_16x16x32_bf16 v[108:111], v[132:135], v[172:175], v[108:111]
	v_mfma_f32_16x16x32_bf16 v[104:107], v[140:143], v[172:175], v[104:107]
	v_mfma_f32_16x16x32_bf16 v[92:95], v[132:135], v[180:183], v[92:95]
	v_mfma_f32_16x16x32_bf16 v[88:91], v[140:143], v[180:183], v[88:91]
	v_mfma_f32_16x16x32_bf16 v[76:79], v[132:135], v[188:191], v[76:79]
	v_mfma_f32_16x16x32_bf16 v[72:75], v[140:143], v[188:191], v[72:75]
	s_setprio 0
	s_setprio 1
	v_mfma_f32_16x16x32_bf16 v[116:119], v[144:147], v[160:163], v[116:119]
	v_mfma_f32_16x16x32_bf16 v[112:115], v[152:155], v[160:163], v[112:115]
	v_mfma_f32_16x16x32_bf16 v[100:103], v[144:147], v[168:171], v[100:103]
	v_mfma_f32_16x16x32_bf16 v[96:99], v[152:155], v[168:171], v[96:99]
	v_mfma_f32_16x16x32_bf16 v[84:87], v[144:147], v[176:179], v[84:87]
	v_mfma_f32_16x16x32_bf16 v[80:83], v[152:155], v[176:179], v[80:83]
	v_mfma_f32_16x16x32_bf16 v[68:71], v[144:147], v[184:187], v[68:71]
	v_mfma_f32_16x16x32_bf16 v[64:67], v[152:155], v[184:187], v[64:67]
	v_mfma_f32_16x16x32_bf16 v[116:119], v[148:151], v[164:167], v[116:119]
	v_mfma_f32_16x16x32_bf16 v[112:115], v[156:159], v[164:167], v[112:115]
	v_mfma_f32_16x16x32_bf16 v[100:103], v[148:151], v[172:175], v[100:103]
	v_mfma_f32_16x16x32_bf16 v[96:99], v[156:159], v[172:175], v[96:99]
	v_mfma_f32_16x16x32_bf16 v[84:87], v[148:151], v[180:183], v[84:87]
	v_mfma_f32_16x16x32_bf16 v[80:83], v[156:159], v[180:183], v[80:83]
	v_mfma_f32_16x16x32_bf16 v[68:71], v[148:151], v[188:191], v[68:71]
	v_mfma_f32_16x16x32_bf16 v[64:67], v[156:159], v[188:191], v[64:67]
	s_setprio 0
	s_barrier
	s_add_i32 s26, s72, s3
	v_lshl_add_u64 v[214:215], v[214:215], 0, s[10:11]
	s_mov_b32 m0, s26
	ds_read_b128 v[160:163], v227 offset:49152
	ds_read_b128 v[164:167], v227 offset:50176
	ds_read_b128 v[168:171], v227 offset:51200
	ds_read_b128 v[172:175], v227 offset:52224
	ds_read_b128 v[176:179], v227 offset:53248
	ds_read_b128 v[180:183], v227 offset:54272
	ds_read_b128 v[184:187], v227 offset:55296
	ds_read_b128 v[188:191], v227 offset:56320
	global_load_lds_dwordx4 v[214:215], off
	s_add_i32 m0, s26, 0x2000
	s_add_u32 s26, s50, 0x40080
	v_lshl_add_u64 v[214:215], v[216:217], 0, s[10:11]
	s_addc_u32 s27, s51, 0
	s_add_i32 s50, s73, s3
	global_load_lds_dwordx4 v[214:215], off
	v_lshl_add_u64 v[214:215], s[26:27], 0, v[194:195]
	s_mov_b32 m0, s50
	s_nop 0
	global_load_lds_dwordx4 v[214:215], off
	v_lshl_add_u64 v[214:215], s[26:27], 0, v[198:199]
	s_add_i32 m0, s50, 0x2000
	s_nop 0
	global_load_lds_dwordx4 v[214:215], off
	v_lshl_add_u64 v[214:215], v[218:219], 0, s[10:11]
	s_mov_b32 m0, s33
	s_nop 0
	global_load_lds_dwordx4 v[214:215], off
	v_lshl_add_u64 v[214:215], v[228:229], 0, s[10:11]
	s_mov_b32 m0, s66
	s_nop 0
	global_load_lds_dwordx4 v[214:215], off
	s_waitcnt vmcnt(8)
	s_waitcnt lgkmcnt(0)
	s_barrier
	s_setprio 1
	s_waitcnt lgkmcnt(0)
	v_mfma_f32_16x16x32_bf16 v[60:63], v[128:131], v[160:163], v[60:63]
	v_mfma_f32_16x16x32_bf16 v[56:59], v[136:139], v[160:163], v[56:59]
	v_mfma_f32_16x16x32_bf16 v[48:51], v[128:131], v[168:171], v[48:51]
	v_mfma_f32_16x16x32_bf16 v[40:43], v[136:139], v[168:171], v[40:43]
	v_mfma_f32_16x16x32_bf16 v[32:35], v[128:131], v[176:179], v[32:35]
	v_mfma_f32_16x16x32_bf16 v[24:27], v[136:139], v[176:179], v[24:27]
	v_mfma_f32_16x16x32_bf16 v[16:19], v[128:131], v[184:187], v[16:19]
	v_mfma_f32_16x16x32_bf16 v[8:11], v[136:139], v[184:187], v[8:11]
	v_mfma_f32_16x16x32_bf16 v[60:63], v[132:135], v[164:167], v[60:63]
	v_mfma_f32_16x16x32_bf16 v[56:59], v[140:143], v[164:167], v[56:59]
	v_mfma_f32_16x16x32_bf16 v[48:51], v[132:135], v[172:175], v[48:51]
	v_mfma_f32_16x16x32_bf16 v[40:43], v[140:143], v[172:175], v[40:43]
	v_mfma_f32_16x16x32_bf16 v[32:35], v[132:135], v[180:183], v[32:35]
	v_mfma_f32_16x16x32_bf16 v[24:27], v[140:143], v[180:183], v[24:27]
	v_mfma_f32_16x16x32_bf16 v[16:19], v[132:135], v[188:191], v[16:19]
	v_mfma_f32_16x16x32_bf16 v[8:11], v[140:143], v[188:191], v[8:11]
	s_setprio 0
	s_setprio 1
	v_mfma_f32_16x16x32_bf16 v[52:55], v[144:147], v[160:163], v[52:55]
	v_mfma_f32_16x16x32_bf16 v[44:47], v[152:155], v[160:163], v[44:47]
	v_mfma_f32_16x16x32_bf16 v[36:39], v[144:147], v[168:171], v[36:39]
	v_mfma_f32_16x16x32_bf16 v[28:31], v[152:155], v[168:171], v[28:31]
	v_mfma_f32_16x16x32_bf16 v[20:23], v[144:147], v[176:179], v[20:23]
	v_mfma_f32_16x16x32_bf16 v[12:15], v[152:155], v[176:179], v[12:15]
	v_mfma_f32_16x16x32_bf16 v[4:7], v[144:147], v[184:187], v[4:7]
	v_mfma_f32_16x16x32_bf16 v[0:3], v[152:155], v[184:187], v[0:3]
	v_mfma_f32_16x16x32_bf16 v[52:55], v[148:151], v[164:167], v[52:55]
	v_mfma_f32_16x16x32_bf16 v[44:47], v[156:159], v[164:167], v[44:47]
	v_mfma_f32_16x16x32_bf16 v[36:39], v[148:151], v[172:175], v[36:39]
	v_mfma_f32_16x16x32_bf16 v[28:31], v[156:159], v[172:175], v[28:31]
	v_mfma_f32_16x16x32_bf16 v[20:23], v[148:151], v[180:183], v[20:23]
	v_mfma_f32_16x16x32_bf16 v[12:15], v[156:159], v[180:183], v[12:15]
	v_mfma_f32_16x16x32_bf16 v[4:7], v[148:151], v[188:191], v[4:7]
	v_mfma_f32_16x16x32_bf16 v[0:3], v[156:159], v[188:191], v[0:3]
	s_setprio 0
	s_barrier
	s_add_i32 vcc_lo, vcc_lo, 2
	s_add_u32 s48, s48, 0x100
	s_addc_u32 s49, s49, 0
	s_add_u32 s96, s96, 0x100
	s_addc_u32 s97, s97, 0
	s_cmp_gt_u32 vcc_lo, 13
	s_cbranch_scc0 .LBB0_341
	s_and_b64 vcc, exec, s[12:13]
	s_cbranch_vccz .LBB0_344
	s_barrier

.LBB0_568:
	ds_read_b128 v[156:159], v150
	ds_read_b128 v[160:163], v150 offset:1024
	ds_read_b128 v[164:167], v150 offset:2048
	ds_read_b128 v[168:171], v150 offset:3072
	ds_read_b128 v[172:175], v151
	ds_read_b128 v[176:179], v151 offset:1024
	ds_read_b128 v[180:183], v151 offset:2048
	ds_read_b128 v[184:187], v151 offset:3072
	s_add_u32 s22, s20, 0xfffd8080
	s_addc_u32 s23, s21, -1
	s_cmp_eq_u32 s53, 6
	s_cselect_b32 s27, s17, s23
	s_cselect_b32 s26, s16, s22
	s_cselect_b32 s23, s19, s52
	s_cselect_b32 s22, s18, s51
	s_mov_b32 m0, s36
	v_lshl_add_u64 v[142:143], s[20:21], 0, v[138:139]
	ds_read_b128 v[188:191], v152
	ds_read_b128 v[192:195], v152 offset:1024
	ds_read_b128 v[196:199], v152 offset:2048
	ds_read_b128 v[200:203], v152 offset:3072
	ds_read_b128 v[204:207], v152 offset:4096
	ds_read_b128 v[208:211], v152 offset:5120
	ds_read_b128 v[212:215], v152 offset:6144
	ds_read_b128 v[216:219], v152 offset:7168
	global_load_lds_dwordx4 v[142:143], off
	v_lshl_add_u64 v[142:143], s[20:21], 0, v[140:141]
	s_mov_b32 m0, s37
	s_nop 0
	global_load_lds_dwordx4 v[142:143], off
	s_waitcnt vmcnt(8)
	s_waitcnt lgkmcnt(0)
	s_barrier
	s_setprio 1
	s_waitcnt lgkmcnt(0)
	s_nop 0
	v_mfma_f32_16x16x32_bf16 v[124:127], v[156:159], v[188:191], v[124:127]
	v_mfma_f32_16x16x32_bf16 v[120:123], v[164:167], v[188:191], v[120:123]
	v_mfma_f32_16x16x32_bf16 v[108:111], v[156:159], v[196:199], v[108:111]
	v_mfma_f32_16x16x32_bf16 v[104:107], v[164:167], v[196:199], v[104:107]
	v_mfma_f32_16x16x32_bf16 v[92:95], v[156:159], v[204:207], v[92:95]
	v_mfma_f32_16x16x32_bf16 v[88:91], v[164:167], v[204:207], v[88:91]
	v_mfma_f32_16x16x32_bf16 v[76:79], v[156:159], v[212:215], v[76:79]
	v_mfma_f32_16x16x32_bf16 v[72:75], v[164:167], v[212:215], v[72:75]
	v_mfma_f32_16x16x32_bf16 v[124:127], v[160:163], v[192:195], v[124:127]
	v_mfma_f32_16x16x32_bf16 v[120:123], v[168:171], v[192:195], v[120:123]
	v_mfma_f32_16x16x32_bf16 v[108:111], v[160:163], v[200:203], v[108:111]
	v_mfma_f32_16x16x32_bf16 v[104:107], v[168:171], v[200:203], v[104:107]
	v_mfma_f32_16x16x32_bf16 v[92:95], v[160:163], v[208:211], v[92:95]
	v_mfma_f32_16x16x32_bf16 v[88:91], v[168:171], v[208:211], v[88:91]
	v_mfma_f32_16x16x32_bf16 v[76:79], v[160:163], v[216:219], v[76:79]
	v_mfma_f32_16x16x32_bf16 v[72:75], v[168:171], v[216:219], v[72:75]
	s_setprio 0
	s_setprio 1
	v_mfma_f32_16x16x32_bf16 v[116:119], v[172:175], v[188:191], v[116:119]
	v_mfma_f32_16x16x32_bf16 v[112:115], v[180:183], v[188:191], v[112:115]
	v_mfma_f32_16x16x32_bf16 v[100:103], v[172:175], v[196:199], v[100:103]
	v_mfma_f32_16x16x32_bf16 v[96:99], v[180:183], v[196:199], v[96:99]
	v_mfma_f32_16x16x32_bf16 v[84:87], v[172:175], v[204:207], v[84:87]
	v_mfma_f32_16x16x32_bf16 v[80:83], v[180:183], v[204:207], v[80:83]
	v_mfma_f32_16x16x32_bf16 v[68:71], v[172:175], v[212:215], v[68:71]
	v_mfma_f32_16x16x32_bf16 v[64:67], v[180:183], v[212:215], v[64:67]
	v_mfma_f32_16x16x32_bf16 v[116:119], v[176:179], v[192:195], v[116:119]
	v_mfma_f32_16x16x32_bf16 v[112:115], v[184:187], v[192:195], v[112:115]
	v_mfma_f32_16x16x32_bf16 v[100:103], v[176:179], v[200:203], v[100:103]
	v_mfma_f32_16x16x32_bf16 v[96:99], v[184:187], v[200:203], v[96:99]
	v_mfma_f32_16x16x32_bf16 v[84:87], v[176:179], v[208:211], v[84:87]
	v_mfma_f32_16x16x32_bf16 v[80:83], v[184:187], v[208:211], v[80:83]
	v_mfma_f32_16x16x32_bf16 v[68:71], v[176:179], v[216:219], v[68:71]
	v_mfma_f32_16x16x32_bf16 v[64:67], v[184:187], v[216:219], v[64:67]
	s_setprio 0
	s_barrier
	s_mov_b32 m0, s38
	v_lshl_add_u64 v[142:143], s[22:23], 0, v[132:133]
	s_add_u32 s54, s22, 0x28000
	ds_read_b128 v[188:191], v152 offset:16384
	ds_read_b128 v[192:195], v152 offset:17408
	ds_read_b128 v[196:199], v152 offset:18432
	ds_read_b128 v[200:203], v152 offset:19456
	ds_read_b128 v[204:207], v152 offset:20480
	ds_read_b128 v[208:211], v152 offset:21504
	ds_read_b128 v[212:215], v152 offset:22528
	ds_read_b128 v[216:219], v152 offset:23552
	global_load_lds_dwordx4 v[142:143], off
	v_lshl_add_u64 v[222:223], s[22:23], 0, v[128:129]
	s_mov_b32 m0, s39
	s_addc_u32 s55, s23, 0
	global_load_lds_dwordx4 v[222:223], off
	v_lshl_add_u64 v[224:225], s[54:55], 0, v[132:133]
	s_mov_b32 m0, s40
	v_lshl_add_u64 v[226:227], s[26:27], 0, v[130:131]
	global_load_lds_dwordx4 v[224:225], off
	v_lshl_add_u64 v[224:225], s[54:55], 0, v[128:129]
	s_mov_b32 m0, s41
	s_nop 0
	global_load_lds_dwordx4 v[224:225], off
	v_lshl_add_u64 v[224:225], s[26:27], 0, v[134:135]
	s_mov_b32 m0, s3
	s_nop 0
	global_load_lds_dwordx4 v[224:225], off
	s_mov_b32 m0, s28
	s_nop 0
	global_load_lds_dwordx4 v[226:227], off
	s_waitcnt vmcnt(8)
	s_waitcnt lgkmcnt(0)
	s_barrier
	s_setprio 1
	s_waitcnt lgkmcnt(0)
	s_nop 0
	v_mfma_f32_16x16x32_bf16 v[60:63], v[156:159], v[188:191], v[60:63]
	v_mfma_f32_16x16x32_bf16 v[56:59], v[164:167], v[188:191], v[56:59]
	v_mfma_f32_16x16x32_bf16 v[44:47], v[156:159], v[196:199], v[44:47]
	v_mfma_f32_16x16x32_bf16 v[40:43], v[164:167], v[196:199], v[40:43]
	v_mfma_f32_16x16x32_bf16 v[28:31], v[156:159], v[204:207], v[28:31]
	v_mfma_f32_16x16x32_bf16 v[24:27], v[164:167], v[204:207], v[24:27]
	v_mfma_f32_16x16x32_bf16 v[12:15], v[156:159], v[212:215], v[12:15]
	v_mfma_f32_16x16x32_bf16 v[8:11], v[164:167], v[212:215], v[8:11]
	v_mfma_f32_16x16x32_bf16 v[60:63], v[160:163], v[192:195], v[60:63]
	v_mfma_f32_16x16x32_bf16 v[56:59], v[168:171], v[192:195], v[56:59]
	v_mfma_f32_16x16x32_bf16 v[44:47], v[160:163], v[200:203], v[44:47]
	v_mfma_f32_16x16x32_bf16 v[40:43], v[168:171], v[200:203], v[40:43]
	v_mfma_f32_16x16x32_bf16 v[28:31], v[160:163], v[208:211], v[28:31]
	v_mfma_f32_16x16x32_bf16 v[24:27], v[168:171], v[208:211], v[24:27]
	v_mfma_f32_16x16x32_bf16 v[12:15], v[160:163], v[216:219], v[12:15]
	v_mfma_f32_16x16x32_bf16 v[8:11], v[168:171], v[216:219], v[8:11]
	s_setprio 0
	s_setprio 1
	v_mfma_f32_16x16x32_bf16 v[52:55], v[172:175], v[188:191], v[52:55]
	v_mfma_f32_16x16x32_bf16 v[48:51], v[180:183], v[188:191], v[48:51]
	v_mfma_f32_16x16x32_bf16 v[36:39], v[172:175], v[196:199], v[36:39]
	v_mfma_f32_16x16x32_bf16 v[32:35], v[180:183], v[196:199], v[32:35]
	v_mfma_f32_16x16x32_bf16 v[20:23], v[172:175], v[204:207], v[20:23]
	v_mfma_f32_16x16x32_bf16 v[16:19], v[180:183], v[204:207], v[16:19]
	v_mfma_f32_16x16x32_bf16 v[4:7], v[172:175], v[212:215], v[4:7]
	v_mfma_f32_16x16x32_bf16 v[0:3], v[180:183], v[212:215], v[0:3]
	v_mfma_f32_16x16x32_bf16 v[52:55], v[176:179], v[192:195], v[52:55]
	v_mfma_f32_16x16x32_bf16 v[48:51], v[184:187], v[192:195], v[48:51]
	v_mfma_f32_16x16x32_bf16 v[36:39], v[176:179], v[200:203], v[36:39]
	v_mfma_f32_16x16x32_bf16 v[32:35], v[184:187], v[200:203], v[32:35]
	v_mfma_f32_16x16x32_bf16 v[20:23], v[176:179], v[208:211], v[20:23]
	v_mfma_f32_16x16x32_bf16 v[16:19], v[184:187], v[208:211], v[16:19]
	v_mfma_f32_16x16x32_bf16 v[4:7], v[176:179], v[216:219], v[4:7]
	v_mfma_f32_16x16x32_bf16 v[0:3], v[184:187], v[216:219], v[0:3]
	s_setprio 0
	s_barrier
	ds_read_b128 v[156:159], v153
	ds_read_b128 v[160:163], v153 offset:1024
	ds_read_b128 v[164:167], v153 offset:2048
	ds_read_b128 v[168:171], v153 offset:3072
	ds_read_b128 v[172:175], v154
	ds_read_b128 v[176:179], v154 offset:1024
	ds_read_b128 v[180:183], v154 offset:2048
	ds_read_b128 v[184:187], v154 offset:3072
	s_add_u32 s26, s26, 0x28000
	s_addc_u32 s27, s27, 0
	s_mov_b32 m0, s29
	v_lshl_add_u64 v[228:229], s[26:27], 0, v[134:135]
	ds_read_b128 v[188:191], v152 offset:32768
	ds_read_b128 v[192:195], v152 offset:33792
	ds_read_b128 v[196:199], v152 offset:34816
	ds_read_b128 v[200:203], v152 offset:35840
	ds_read_b128 v[204:207], v152 offset:36864
	ds_read_b128 v[208:211], v152 offset:37888
	ds_read_b128 v[212:215], v152 offset:38912
	ds_read_b128 v[216:219], v152 offset:39936
	global_load_lds_dwordx4 v[228:229], off
	v_lshl_add_u64 v[228:229], s[26:27], 0, v[130:131]
	s_mov_b32 m0, s30
	s_nop 0
	global_load_lds_dwordx4 v[228:229], off
	s_waitcnt vmcnt(8)
	s_waitcnt lgkmcnt(0)
	s_barrier
	s_setprio 1
	s_waitcnt lgkmcnt(0)
	s_nop 0
	v_mfma_f32_16x16x32_bf16 v[124:127], v[156:159], v[188:191], v[124:127]
	v_mfma_f32_16x16x32_bf16 v[120:123], v[164:167], v[188:191], v[120:123]
	v_mfma_f32_16x16x32_bf16 v[108:111], v[156:159], v[196:199], v[108:111]
	v_mfma_f32_16x16x32_bf16 v[104:107], v[164:167], v[196:199], v[104:107]
	v_mfma_f32_16x16x32_bf16 v[92:95], v[156:159], v[204:207], v[92:95]
	v_mfma_f32_16x16x32_bf16 v[88:91], v[164:167], v[204:207], v[88:91]
	v_mfma_f32_16x16x32_bf16 v[76:79], v[156:159], v[212:215], v[76:79]
	v_mfma_f32_16x16x32_bf16 v[72:75], v[164:167], v[212:215], v[72:75]
	v_mfma_f32_16x16x32_bf16 v[124:127], v[160:163], v[192:195], v[124:127]
	v_mfma_f32_16x16x32_bf16 v[120:123], v[168:171], v[192:195], v[120:123]
	v_mfma_f32_16x16x32_bf16 v[108:111], v[160:163], v[200:203], v[108:111]
	v_mfma_f32_16x16x32_bf16 v[104:107], v[168:171], v[200:203], v[104:107]
	v_mfma_f32_16x16x32_bf16 v[92:95], v[160:163], v[208:211], v[92:95]
	v_mfma_f32_16x16x32_bf16 v[88:91], v[168:171], v[208:211], v[88:91]
	v_mfma_f32_16x16x32_bf16 v[76:79], v[160:163], v[216:219], v[76:79]
	v_mfma_f32_16x16x32_bf16 v[72:75], v[168:171], v[216:219], v[72:75]
	s_setprio 0
	s_setprio 1
	v_mfma_f32_16x16x32_bf16 v[116:119], v[172:175], v[188:191], v[116:119]
	v_mfma_f32_16x16x32_bf16 v[112:115], v[180:183], v[188:191], v[112:115]
	v_mfma_f32_16x16x32_bf16 v[100:103], v[172:175], v[196:199], v[100:103]
	v_mfma_f32_16x16x32_bf16 v[96:99], v[180:183], v[196:199], v[96:99]
	v_mfma_f32_16x16x32_bf16 v[84:87], v[172:175], v[204:207], v[84:87]
	v_mfma_f32_16x16x32_bf16 v[80:83], v[180:183], v[204:207], v[80:83]
	v_mfma_f32_16x16x32_bf16 v[68:71], v[172:175], v[212:215], v[68:71]
	v_mfma_f32_16x16x32_bf16 v[64:67], v[180:183], v[212:215], v[64:67]
	v_mfma_f32_16x16x32_bf16 v[116:119], v[176:179], v[192:195], v[116:119]
	v_mfma_f32_16x16x32_bf16 v[112:115], v[184:187], v[192:195], v[112:115]
	v_mfma_f32_16x16x32_bf16 v[100:103], v[176:179], v[200:203], v[100:103]
	v_mfma_f32_16x16x32_bf16 v[96:99], v[184:187], v[200:203], v[96:99]
	v_mfma_f32_16x16x32_bf16 v[84:87], v[176:179], v[208:211], v[84:87]
	v_mfma_f32_16x16x32_bf16 v[80:83], v[184:187], v[208:211], v[80:83]
	v_mfma_f32_16x16x32_bf16 v[68:71], v[176:179], v[216:219], v[68:71]
	v_mfma_f32_16x16x32_bf16 v[64:67], v[184:187], v[216:219], v[64:67]
	s_setprio 0
	s_barrier
	s_mov_b32 m0, s42
	v_lshl_add_u64 v[142:143], v[142:143], 0, s[6:7]
	s_add_u32 s22, s22, 0x28080
	ds_read_b128 v[188:191], v152 offset:49152
	ds_read_b128 v[192:195], v152 offset:50176
	ds_read_b128 v[196:199], v152 offset:51200
	ds_read_b128 v[200:203], v152 offset:52224
	ds_read_b128 v[204:207], v152 offset:53248
	ds_read_b128 v[208:211], v152 offset:54272
	ds_read_b128 v[212:215], v152 offset:55296
	ds_read_b128 v[216:219], v152 offset:56320
	global_load_lds_dwordx4 v[142:143], off
	v_lshl_add_u64 v[142:143], v[222:223], 0, s[6:7]
	s_mov_b32 m0, s43
	s_addc_u32 s23, s23, 0
	global_load_lds_dwordx4 v[142:143], off
	v_lshl_add_u64 v[142:143], s[22:23], 0, v[132:133]
	s_mov_b32 m0, s44
	s_nop 0
	global_load_lds_dwordx4 v[142:143], off
	v_lshl_add_u64 v[142:143], s[22:23], 0, v[128:129]
	s_mov_b32 m0, s45
	s_nop 0
	global_load_lds_dwordx4 v[142:143], off
	v_lshl_add_u64 v[142:143], v[224:225], 0, s[6:7]
	s_mov_b32 m0, s34
	s_nop 0
	global_load_lds_dwordx4 v[142:143], off
	v_lshl_add_u64 v[142:143], v[226:227], 0, s[6:7]
	s_mov_b32 m0, s35
	s_nop 0
	global_load_lds_dwordx4 v[142:143], off
	s_waitcnt vmcnt(8)
	s_waitcnt lgkmcnt(0)
	s_barrier
	s_setprio 1
	s_waitcnt lgkmcnt(0)
	v_mfma_f32_16x16x32_bf16 v[60:63], v[156:159], v[188:191], v[60:63]
	v_mfma_f32_16x16x32_bf16 v[56:59], v[164:167], v[188:191], v[56:59]
	v_mfma_f32_16x16x32_bf16 v[44:47], v[156:159], v[196:199], v[44:47]
	v_mfma_f32_16x16x32_bf16 v[40:43], v[164:167], v[196:199], v[40:43]
	v_mfma_f32_16x16x32_bf16 v[28:31], v[156:159], v[204:207], v[28:31]
	v_mfma_f32_16x16x32_bf16 v[24:27], v[164:167], v[204:207], v[24:27]
	v_mfma_f32_16x16x32_bf16 v[12:15], v[156:159], v[212:215], v[12:15]
	v_mfma_f32_16x16x32_bf16 v[8:11], v[164:167], v[212:215], v[8:11]
	v_mfma_f32_16x16x32_bf16 v[60:63], v[160:163], v[192:195], v[60:63]
	v_mfma_f32_16x16x32_bf16 v[56:59], v[168:171], v[192:195], v[56:59]
	v_mfma_f32_16x16x32_bf16 v[44:47], v[160:163], v[200:203], v[44:47]
	v_mfma_f32_16x16x32_bf16 v[40:43], v[168:171], v[200:203], v[40:43]
	v_mfma_f32_16x16x32_bf16 v[28:31], v[160:163], v[208:211], v[28:31]
	v_mfma_f32_16x16x32_bf16 v[24:27], v[168:171], v[208:211], v[24:27]
	v_mfma_f32_16x16x32_bf16 v[12:15], v[160:163], v[216:219], v[12:15]
	v_mfma_f32_16x16x32_bf16 v[8:11], v[168:171], v[216:219], v[8:11]
	s_setprio 0
	s_setprio 1
	v_mfma_f32_16x16x32_bf16 v[52:55], v[172:175], v[188:191], v[52:55]
	v_mfma_f32_16x16x32_bf16 v[48:51], v[180:183], v[188:191], v[48:51]
	v_mfma_f32_16x16x32_bf16 v[36:39], v[172:175], v[196:199], v[36:39]
	v_mfma_f32_16x16x32_bf16 v[32:35], v[180:183], v[196:199], v[32:35]
	v_mfma_f32_16x16x32_bf16 v[20:23], v[172:175], v[204:207], v[20:23]
	v_mfma_f32_16x16x32_bf16 v[16:19], v[180:183], v[204:207], v[16:19]
	v_mfma_f32_16x16x32_bf16 v[4:7], v[172:175], v[212:215], v[4:7]
	v_mfma_f32_16x16x32_bf16 v[0:3], v[180:183], v[212:215], v[0:3]
	v_mfma_f32_16x16x32_bf16 v[52:55], v[176:179], v[192:195], v[52:55]
	v_mfma_f32_16x16x32_bf16 v[48:51], v[184:187], v[192:195], v[48:51]
	v_mfma_f32_16x16x32_bf16 v[36:39], v[176:179], v[200:203], v[36:39]
	v_mfma_f32_16x16x32_bf16 v[32:35], v[184:187], v[200:203], v[32:35]
	v_mfma_f32_16x16x32_bf16 v[20:23], v[176:179], v[208:211], v[20:23]
	v_mfma_f32_16x16x32_bf16 v[16:19], v[184:187], v[208:211], v[16:19]
	v_mfma_f32_16x16x32_bf16 v[4:7], v[176:179], v[216:219], v[4:7]
	v_mfma_f32_16x16x32_bf16 v[0:3], v[184:187], v[216:219], v[0:3]
	s_setprio 0
	s_barrier
	s_add_i32 s53, s53, 2
	s_add_u32 s20, s20, 0x100
	s_addc_u32 s21, s21, 0
	s_add_u32 s51, s51, 0x100
	s_addc_u32 s52, s52, 0
	s_cmp_gt_u32 s53, 7
	s_cbranch_scc0 .LBB0_568
	s_and_b64 vcc, exec, s[8:9]
	s_cbranch_vccz .LBB0_571
	s_barrier

.LBB0_649:
	ds_read_b128 v[152:155], v149
	ds_read_b128 v[156:159], v149 offset:1024
	ds_read_b128 v[160:163], v149 offset:2048
	ds_read_b128 v[164:167], v149 offset:3072
	ds_read_b128 v[168:171], v150
	ds_read_b128 v[172:175], v150 offset:1024
	ds_read_b128 v[176:179], v150 offset:2048
	ds_read_b128 v[180:183], v150 offset:3072
	s_add_u32 s24, s22, 0xfffe0080
	s_addc_u32 s25, s23, -1
	s_cmp_eq_u32 s48, 4
	s_cselect_b32 s27, s15, s25
	s_cselect_b32 s26, s44, s24
	s_cselect_b32 s25, s13, s47
	s_cselect_b32 s24, s45, s46
	v_lshl_add_u64 v[144:145], s[22:23], 0, v[136:137]
	s_add_i32 m0, s21, 0xc000
	ds_read_b128 v[184:187], v151
	ds_read_b128 v[188:191], v151 offset:1024
	ds_read_b128 v[192:195], v151 offset:2048
	ds_read_b128 v[196:199], v151 offset:3072
	ds_read_b128 v[200:203], v151 offset:4096
	ds_read_b128 v[204:207], v151 offset:5120
	ds_read_b128 v[208:211], v151 offset:6144
	ds_read_b128 v[212:215], v151 offset:7168
	global_load_lds_dwordx4 v[144:145], off
	v_lshl_add_u64 v[144:145], s[22:23], 0, v[138:139]
	s_add_i32 m0, s21, 0xe000
	s_nop 0
	global_load_lds_dwordx4 v[144:145], off
	s_waitcnt vmcnt(8)
	s_waitcnt lgkmcnt(0)
	s_barrier
	s_setprio 1
	s_waitcnt lgkmcnt(0)
	v_mfma_f32_16x16x32_bf16 v[124:127], v[152:155], v[184:187], v[124:127]
	v_mfma_f32_16x16x32_bf16 v[120:123], v[160:163], v[184:187], v[120:123]
	v_mfma_f32_16x16x32_bf16 v[108:111], v[152:155], v[192:195], v[108:111]
	v_mfma_f32_16x16x32_bf16 v[104:107], v[160:163], v[192:195], v[104:107]
	v_mfma_f32_16x16x32_bf16 v[92:95], v[152:155], v[200:203], v[92:95]
	v_mfma_f32_16x16x32_bf16 v[88:91], v[160:163], v[200:203], v[88:91]
	v_mfma_f32_16x16x32_bf16 v[76:79], v[152:155], v[208:211], v[76:79]
	v_mfma_f32_16x16x32_bf16 v[72:75], v[160:163], v[208:211], v[72:75]
	v_mfma_f32_16x16x32_bf16 v[124:127], v[156:159], v[188:191], v[124:127]
	v_mfma_f32_16x16x32_bf16 v[120:123], v[164:167], v[188:191], v[120:123]
	v_mfma_f32_16x16x32_bf16 v[108:111], v[156:159], v[196:199], v[108:111]
	v_mfma_f32_16x16x32_bf16 v[104:107], v[164:167], v[196:199], v[104:107]
	v_mfma_f32_16x16x32_bf16 v[92:95], v[156:159], v[204:207], v[92:95]
	v_mfma_f32_16x16x32_bf16 v[88:91], v[164:167], v[204:207], v[88:91]
	v_mfma_f32_16x16x32_bf16 v[76:79], v[156:159], v[212:215], v[76:79]
	v_mfma_f32_16x16x32_bf16 v[72:75], v[164:167], v[212:215], v[72:75]
	s_setprio 0
	s_setprio 1
	v_mfma_f32_16x16x32_bf16 v[116:119], v[168:171], v[184:187], v[116:119]
	v_mfma_f32_16x16x32_bf16 v[112:115], v[176:179], v[184:187], v[112:115]
	v_mfma_f32_16x16x32_bf16 v[100:103], v[168:171], v[192:195], v[100:103]
	v_mfma_f32_16x16x32_bf16 v[96:99], v[176:179], v[192:195], v[96:99]
	v_mfma_f32_16x16x32_bf16 v[84:87], v[168:171], v[200:203], v[84:87]
	v_mfma_f32_16x16x32_bf16 v[80:83], v[176:179], v[200:203], v[80:83]
	v_mfma_f32_16x16x32_bf16 v[68:71], v[168:171], v[208:211], v[68:71]
	v_mfma_f32_16x16x32_bf16 v[64:67], v[176:179], v[208:211], v[64:67]
	v_mfma_f32_16x16x32_bf16 v[116:119], v[172:175], v[188:191], v[116:119]
	v_mfma_f32_16x16x32_bf16 v[112:115], v[180:183], v[188:191], v[112:115]
	v_mfma_f32_16x16x32_bf16 v[100:103], v[172:175], v[196:199], v[100:103]
	v_mfma_f32_16x16x32_bf16 v[96:99], v[180:183], v[196:199], v[96:99]
	v_mfma_f32_16x16x32_bf16 v[84:87], v[172:175], v[204:207], v[84:87]
	v_mfma_f32_16x16x32_bf16 v[80:83], v[180:183], v[204:207], v[80:83]
	v_mfma_f32_16x16x32_bf16 v[68:71], v[172:175], v[212:215], v[68:71]
	v_mfma_f32_16x16x32_bf16 v[64:67], v[180:183], v[212:215], v[64:67]
	s_setprio 0
	s_barrier
	s_add_i32 s49, s38, s3
	v_lshl_add_u64 v[144:145], s[24:25], 0, v[130:131]
	s_mov_b32 m0, s49
	ds_read_b128 v[184:187], v151 offset:16384
	ds_read_b128 v[188:191], v151 offset:17408
	ds_read_b128 v[192:195], v151 offset:18432
	ds_read_b128 v[196:199], v151 offset:19456
	ds_read_b128 v[200:203], v151 offset:20480
	ds_read_b128 v[204:207], v151 offset:21504
	ds_read_b128 v[208:211], v151 offset:22528
	ds_read_b128 v[212:215], v151 offset:23552
	global_load_lds_dwordx4 v[144:145], off
	s_add_i32 m0, s49, 0x2000
	s_add_u32 s50, s24, 0x20000
	v_lshl_add_u64 v[216:217], s[24:25], 0, v[134:135]
	s_addc_u32 s51, s25, 0
	s_add_i32 s49, s39, s3
	global_load_lds_dwordx4 v[216:217], off
	v_lshl_add_u64 v[218:219], s[50:51], 0, v[130:131]
	s_mov_b32 m0, s49
	v_lshl_add_u64 v[222:223], s[26:27], 0, v[132:133]
	global_load_lds_dwordx4 v[218:219], off
	v_lshl_add_u64 v[218:219], s[50:51], 0, v[134:135]
	s_add_i32 m0, s49, 0x2000
	s_nop 0
	global_load_lds_dwordx4 v[218:219], off
	v_lshl_add_u64 v[218:219], s[26:27], 0, v[128:129]
	s_mov_b32 m0, s21
	s_nop 0
	global_load_lds_dwordx4 v[218:219], off
	s_mov_b32 m0, s29
	s_nop 0
	global_load_lds_dwordx4 v[222:223], off
	s_waitcnt vmcnt(8)
	s_waitcnt lgkmcnt(0)
	s_barrier
	s_setprio 1
	s_waitcnt lgkmcnt(0)
	s_nop 0
	v_mfma_f32_16x16x32_bf16 v[60:63], v[152:155], v[184:187], v[60:63]
	v_mfma_f32_16x16x32_bf16 v[56:59], v[160:163], v[184:187], v[56:59]
	v_mfma_f32_16x16x32_bf16 v[44:47], v[152:155], v[192:195], v[44:47]
	v_mfma_f32_16x16x32_bf16 v[40:43], v[160:163], v[192:195], v[40:43]
	v_mfma_f32_16x16x32_bf16 v[28:31], v[152:155], v[200:203], v[28:31]
	v_mfma_f32_16x16x32_bf16 v[24:27], v[160:163], v[200:203], v[24:27]
	v_mfma_f32_16x16x32_bf16 v[12:15], v[152:155], v[208:211], v[12:15]
	v_mfma_f32_16x16x32_bf16 v[8:11], v[160:163], v[208:211], v[8:11]
	v_mfma_f32_16x16x32_bf16 v[60:63], v[156:159], v[188:191], v[60:63]
	v_mfma_f32_16x16x32_bf16 v[56:59], v[164:167], v[188:191], v[56:59]
	v_mfma_f32_16x16x32_bf16 v[44:47], v[156:159], v[196:199], v[44:47]
	v_mfma_f32_16x16x32_bf16 v[40:43], v[164:167], v[196:199], v[40:43]
	v_mfma_f32_16x16x32_bf16 v[28:31], v[156:159], v[204:207], v[28:31]
	v_mfma_f32_16x16x32_bf16 v[24:27], v[164:167], v[204:207], v[24:27]
	v_mfma_f32_16x16x32_bf16 v[12:15], v[156:159], v[212:215], v[12:15]
	v_mfma_f32_16x16x32_bf16 v[8:11], v[164:167], v[212:215], v[8:11]
	s_setprio 0
	s_setprio 1
	v_mfma_f32_16x16x32_bf16 v[52:55], v[168:171], v[184:187], v[52:55]
	v_mfma_f32_16x16x32_bf16 v[48:51], v[176:179], v[184:187], v[48:51]
	v_mfma_f32_16x16x32_bf16 v[36:39], v[168:171], v[192:195], v[36:39]
	v_mfma_f32_16x16x32_bf16 v[32:35], v[176:179], v[192:195], v[32:35]
	v_mfma_f32_16x16x32_bf16 v[20:23], v[168:171], v[200:203], v[20:23]
	v_mfma_f32_16x16x32_bf16 v[16:19], v[176:179], v[200:203], v[16:19]
	v_mfma_f32_16x16x32_bf16 v[4:7], v[168:171], v[208:211], v[4:7]
	v_mfma_f32_16x16x32_bf16 v[0:3], v[176:179], v[208:211], v[0:3]
	v_mfma_f32_16x16x32_bf16 v[52:55], v[172:175], v[188:191], v[52:55]
	v_mfma_f32_16x16x32_bf16 v[48:51], v[180:183], v[188:191], v[48:51]
	v_mfma_f32_16x16x32_bf16 v[36:39], v[172:175], v[196:199], v[36:39]
	v_mfma_f32_16x16x32_bf16 v[32:35], v[180:183], v[196:199], v[32:35]
	v_mfma_f32_16x16x32_bf16 v[20:23], v[172:175], v[204:207], v[20:23]
	v_mfma_f32_16x16x32_bf16 v[16:19], v[180:183], v[204:207], v[16:19]
	v_mfma_f32_16x16x32_bf16 v[4:7], v[172:175], v[212:215], v[4:7]
	v_mfma_f32_16x16x32_bf16 v[0:3], v[180:183], v[212:215], v[0:3]
	s_setprio 0
	s_barrier
	s_add_i32 s49, 0, 0x18000
	s_add_i32 s50, 0, 0x1c000
	v_add_u32_e32 v164, s49, v147
	v_add_u32_e32 v180, s50, v147
	ds_read_b128 v[152:155], v164
	ds_read_b128 v[156:159], v164 offset:1024
	ds_read_b128 v[160:163], v164 offset:2048
	ds_read_b128 v[164:167], v164 offset:3072
	ds_read_b128 v[168:171], v180
	ds_read_b128 v[172:175], v180 offset:1024
	ds_read_b128 v[176:179], v180 offset:2048
	ds_read_b128 v[180:183], v180 offset:3072
	s_add_u32 s26, s26, 0x20000
	s_addc_u32 s27, s27, 0
	s_mov_b32 m0, s30
	v_lshl_add_u64 v[224:225], s[26:27], 0, v[128:129]
	ds_read_b128 v[184:187], v151 offset:32768
	ds_read_b128 v[188:191], v151 offset:33792
	ds_read_b128 v[192:195], v151 offset:34816
	ds_read_b128 v[196:199], v151 offset:35840
	ds_read_b128 v[200:203], v151 offset:36864
	ds_read_b128 v[204:207], v151 offset:37888
	ds_read_b128 v[208:211], v151 offset:38912
	ds_read_b128 v[212:215], v151 offset:39936
	global_load_lds_dwordx4 v[224:225], off
	v_lshl_add_u64 v[224:225], s[26:27], 0, v[132:133]
	s_mov_b32 m0, s31
	s_nop 0
	global_load_lds_dwordx4 v[224:225], off
	s_waitcnt vmcnt(8)
	s_waitcnt lgkmcnt(0)
	s_barrier
	s_setprio 1
	s_waitcnt lgkmcnt(0)
	s_nop 0
	v_mfma_f32_16x16x32_bf16 v[124:127], v[152:155], v[184:187], v[124:127]
	v_mfma_f32_16x16x32_bf16 v[120:123], v[160:163], v[184:187], v[120:123]
	v_mfma_f32_16x16x32_bf16 v[108:111], v[152:155], v[192:195], v[108:111]
	v_mfma_f32_16x16x32_bf16 v[104:107], v[160:163], v[192:195], v[104:107]
	v_mfma_f32_16x16x32_bf16 v[92:95], v[152:155], v[200:203], v[92:95]
	v_mfma_f32_16x16x32_bf16 v[88:91], v[160:163], v[200:203], v[88:91]
	v_mfma_f32_16x16x32_bf16 v[76:79], v[152:155], v[208:211], v[76:79]
	v_mfma_f32_16x16x32_bf16 v[72:75], v[160:163], v[208:211], v[72:75]
	v_mfma_f32_16x16x32_bf16 v[124:127], v[156:159], v[188:191], v[124:127]
	v_mfma_f32_16x16x32_bf16 v[120:123], v[164:167], v[188:191], v[120:123]
	v_mfma_f32_16x16x32_bf16 v[108:111], v[156:159], v[196:199], v[108:111]
	v_mfma_f32_16x16x32_bf16 v[104:107], v[164:167], v[196:199], v[104:107]
	v_mfma_f32_16x16x32_bf16 v[92:95], v[156:159], v[204:207], v[92:95]
	v_mfma_f32_16x16x32_bf16 v[88:91], v[164:167], v[204:207], v[88:91]
	v_mfma_f32_16x16x32_bf16 v[76:79], v[156:159], v[212:215], v[76:79]
	v_mfma_f32_16x16x32_bf16 v[72:75], v[164:167], v[212:215], v[72:75]
	s_setprio 0
	s_setprio 1
	v_mfma_f32_16x16x32_bf16 v[116:119], v[168:171], v[184:187], v[116:119]
	v_mfma_f32_16x16x32_bf16 v[112:115], v[176:179], v[184:187], v[112:115]
	v_mfma_f32_16x16x32_bf16 v[100:103], v[168:171], v[192:195], v[100:103]
	v_mfma_f32_16x16x32_bf16 v[96:99], v[176:179], v[192:195], v[96:99]
	v_mfma_f32_16x16x32_bf16 v[84:87], v[168:171], v[200:203], v[84:87]
	v_mfma_f32_16x16x32_bf16 v[80:83], v[176:179], v[200:203], v[80:83]
	v_mfma_f32_16x16x32_bf16 v[68:71], v[168:171], v[208:211], v[68:71]
	v_mfma_f32_16x16x32_bf16 v[64:67], v[176:179], v[208:211], v[64:67]
	v_mfma_f32_16x16x32_bf16 v[116:119], v[172:175], v[188:191], v[116:119]
	v_mfma_f32_16x16x32_bf16 v[112:115], v[180:183], v[188:191], v[112:115]
	v_mfma_f32_16x16x32_bf16 v[100:103], v[172:175], v[196:199], v[100:103]
	v_mfma_f32_16x16x32_bf16 v[96:99], v[180:183], v[196:199], v[96:99]
	v_mfma_f32_16x16x32_bf16 v[84:87], v[172:175], v[204:207], v[84:87]
	v_mfma_f32_16x16x32_bf16 v[80:83], v[180:183], v[204:207], v[80:83]
	v_mfma_f32_16x16x32_bf16 v[68:71], v[172:175], v[212:215], v[68:71]
	v_mfma_f32_16x16x32_bf16 v[64:67], v[180:183], v[212:215], v[64:67]
	s_setprio 0
	s_barrier
	s_add_i32 s26, s49, s3
	v_lshl_add_u64 v[144:145], v[144:145], 0, s[8:9]
	s_mov_b32 m0, s26
	ds_read_b128 v[184:187], v151 offset:49152
	ds_read_b128 v[188:191], v151 offset:50176
	ds_read_b128 v[192:195], v151 offset:51200
	ds_read_b128 v[196:199], v151 offset:52224
	ds_read_b128 v[200:203], v151 offset:53248
	ds_read_b128 v[204:207], v151 offset:54272
	ds_read_b128 v[208:211], v151 offset:55296
	ds_read_b128 v[212:215], v151 offset:56320
	global_load_lds_dwordx4 v[144:145], off
	s_add_i32 m0, s26, 0x2000
	s_add_u32 s24, s24, 0x20080
	v_lshl_add_u64 v[144:145], v[216:217], 0, s[8:9]
	s_addc_u32 s25, s25, 0
	s_add_i32 s26, s50, s3
	global_load_lds_dwordx4 v[144:145], off
	v_lshl_add_u64 v[144:145], s[24:25], 0, v[130:131]
	s_mov_b32 m0, s26
	s_nop 0
	global_load_lds_dwordx4 v[144:145], off
	v_lshl_add_u64 v[144:145], s[24:25], 0, v[134:135]
	s_add_i32 m0, s26, 0x2000
	s_nop 0
	global_load_lds_dwordx4 v[144:145], off
	v_lshl_add_u64 v[144:145], v[218:219], 0, s[8:9]
	s_mov_b32 m0, s35
	s_nop 0
	global_load_lds_dwordx4 v[144:145], off
	v_lshl_add_u64 v[144:145], v[222:223], 0, s[8:9]
	s_mov_b32 m0, s36
	s_nop 0
	global_load_lds_dwordx4 v[144:145], off
	s_waitcnt vmcnt(8)
	s_waitcnt lgkmcnt(0)
	s_barrier
	s_setprio 1
	s_waitcnt lgkmcnt(0)
	v_mfma_f32_16x16x32_bf16 v[60:63], v[152:155], v[184:187], v[60:63]
	v_mfma_f32_16x16x32_bf16 v[56:59], v[160:163], v[184:187], v[56:59]
	v_mfma_f32_16x16x32_bf16 v[44:47], v[152:155], v[192:195], v[44:47]
	v_mfma_f32_16x16x32_bf16 v[40:43], v[160:163], v[192:195], v[40:43]
	v_mfma_f32_16x16x32_bf16 v[28:31], v[152:155], v[200:203], v[28:31]
	v_mfma_f32_16x16x32_bf16 v[24:27], v[160:163], v[200:203], v[24:27]
	v_mfma_f32_16x16x32_bf16 v[12:15], v[152:155], v[208:211], v[12:15]
	v_mfma_f32_16x16x32_bf16 v[8:11], v[160:163], v[208:211], v[8:11]
	v_mfma_f32_16x16x32_bf16 v[60:63], v[156:159], v[188:191], v[60:63]
	v_mfma_f32_16x16x32_bf16 v[56:59], v[164:167], v[188:191], v[56:59]
	v_mfma_f32_16x16x32_bf16 v[44:47], v[156:159], v[196:199], v[44:47]
	v_mfma_f32_16x16x32_bf16 v[40:43], v[164:167], v[196:199], v[40:43]
	v_mfma_f32_16x16x32_bf16 v[28:31], v[156:159], v[204:207], v[28:31]
	v_mfma_f32_16x16x32_bf16 v[24:27], v[164:167], v[204:207], v[24:27]
	v_mfma_f32_16x16x32_bf16 v[12:15], v[156:159], v[212:215], v[12:15]
	v_mfma_f32_16x16x32_bf16 v[8:11], v[164:167], v[212:215], v[8:11]
	s_setprio 0
	s_setprio 1
	v_mfma_f32_16x16x32_bf16 v[52:55], v[168:171], v[184:187], v[52:55]
	v_mfma_f32_16x16x32_bf16 v[48:51], v[176:179], v[184:187], v[48:51]
	v_mfma_f32_16x16x32_bf16 v[36:39], v[168:171], v[192:195], v[36:39]
	v_mfma_f32_16x16x32_bf16 v[32:35], v[176:179], v[192:195], v[32:35]
	v_mfma_f32_16x16x32_bf16 v[20:23], v[168:171], v[200:203], v[20:23]
	v_mfma_f32_16x16x32_bf16 v[16:19], v[176:179], v[200:203], v[16:19]
	v_mfma_f32_16x16x32_bf16 v[4:7], v[168:171], v[208:211], v[4:7]
	v_mfma_f32_16x16x32_bf16 v[0:3], v[176:179], v[208:211], v[0:3]
	v_mfma_f32_16x16x32_bf16 v[52:55], v[172:175], v[188:191], v[52:55]
	v_mfma_f32_16x16x32_bf16 v[48:51], v[180:183], v[188:191], v[48:51]
	v_mfma_f32_16x16x32_bf16 v[36:39], v[172:175], v[196:199], v[36:39]
	v_mfma_f32_16x16x32_bf16 v[32:35], v[180:183], v[196:199], v[32:35]
	v_mfma_f32_16x16x32_bf16 v[20:23], v[172:175], v[204:207], v[20:23]
	v_mfma_f32_16x16x32_bf16 v[16:19], v[180:183], v[204:207], v[16:19]
	v_mfma_f32_16x16x32_bf16 v[4:7], v[172:175], v[212:215], v[4:7]
	v_mfma_f32_16x16x32_bf16 v[0:3], v[180:183], v[212:215], v[0:3]
	s_setprio 0
	s_barrier
	s_add_i32 s48, s48, 2
	s_add_u32 s22, s22, 0x100
	s_addc_u32 s23, s23, 0
	s_add_u32 s46, s46, 0x100
	s_addc_u32 s47, s47, 0
	s_cmp_gt_u32 s48, 5
	s_cbranch_scc0 .LBB0_649
	s_and_b64 vcc, exec, s[10:11]
	s_cbranch_vccz .LBB0_652
	s_barrier

.LBB0_726:
	ds_read_b128 v[144:147], v151
	ds_read_b128 v[156:159], v151 offset:1024
	ds_read_b128 v[160:163], v151 offset:2048
	ds_read_b128 v[164:167], v151 offset:3072
	ds_read_b128 v[168:171], v152
	ds_read_b128 v[172:175], v152 offset:1024
	ds_read_b128 v[176:179], v152 offset:2048
	ds_read_b128 v[180:183], v152 offset:3072
	s_add_u32 s34, s30, 0xfffc0080
	s_addc_u32 s35, s31, -1
	s_cmp_eq_u32 s53, 12
	s_cselect_b32 s37, s23, s35
	s_cselect_b32 s36, s29, s34
	s_cselect_b32 s35, s21, s52
	s_cselect_b32 s34, s50, s51
	v_lshl_add_u64 v[216:217], s[30:31], 0, v[136:137]
	s_add_i32 m0, s33, 0xc000
	ds_read_b128 v[184:187], v153
	ds_read_b128 v[188:191], v153 offset:1024
	ds_read_b128 v[192:195], v153 offset:2048
	ds_read_b128 v[196:199], v153 offset:3072
	ds_read_b128 v[200:203], v153 offset:4096
	ds_read_b128 v[204:207], v153 offset:5120
	ds_read_b128 v[208:211], v153 offset:6144
	ds_read_b128 v[212:215], v153 offset:7168
	global_load_lds_dwordx4 v[216:217], off
	v_lshl_add_u64 v[216:217], s[30:31], 0, v[138:139]
	s_add_i32 m0, s33, 0xe000
	s_nop 0
	global_load_lds_dwordx4 v[216:217], off
	s_waitcnt vmcnt(8)
	s_waitcnt lgkmcnt(0)
	s_barrier
	s_setprio 1
	s_waitcnt lgkmcnt(0)
	v_mfma_f32_16x16x32_bf16 v[124:127], v[144:147], v[184:187], v[124:127]
	v_mfma_f32_16x16x32_bf16 v[120:123], v[160:163], v[184:187], v[120:123]
	v_mfma_f32_16x16x32_bf16 v[108:111], v[144:147], v[192:195], v[108:111]
	v_mfma_f32_16x16x32_bf16 v[104:107], v[160:163], v[192:195], v[104:107]
	v_mfma_f32_16x16x32_bf16 v[92:95], v[144:147], v[200:203], v[92:95]
	v_mfma_f32_16x16x32_bf16 v[88:91], v[160:163], v[200:203], v[88:91]
	v_mfma_f32_16x16x32_bf16 v[76:79], v[144:147], v[208:211], v[76:79]
	v_mfma_f32_16x16x32_bf16 v[72:75], v[160:163], v[208:211], v[72:75]
	v_mfma_f32_16x16x32_bf16 v[124:127], v[156:159], v[188:191], v[124:127]
	v_mfma_f32_16x16x32_bf16 v[120:123], v[164:167], v[188:191], v[120:123]
	v_mfma_f32_16x16x32_bf16 v[108:111], v[156:159], v[196:199], v[108:111]
	v_mfma_f32_16x16x32_bf16 v[104:107], v[164:167], v[196:199], v[104:107]
	v_mfma_f32_16x16x32_bf16 v[92:95], v[156:159], v[204:207], v[92:95]
	v_mfma_f32_16x16x32_bf16 v[88:91], v[164:167], v[204:207], v[88:91]
	v_mfma_f32_16x16x32_bf16 v[76:79], v[156:159], v[212:215], v[76:79]
	v_mfma_f32_16x16x32_bf16 v[72:75], v[164:167], v[212:215], v[72:75]
	s_setprio 0
	s_setprio 1
	v_mfma_f32_16x16x32_bf16 v[116:119], v[168:171], v[184:187], v[116:119]
	v_mfma_f32_16x16x32_bf16 v[112:115], v[176:179], v[184:187], v[112:115]
	v_mfma_f32_16x16x32_bf16 v[100:103], v[168:171], v[192:195], v[100:103]
	v_mfma_f32_16x16x32_bf16 v[96:99], v[176:179], v[192:195], v[96:99]
	v_mfma_f32_16x16x32_bf16 v[84:87], v[168:171], v[200:203], v[84:87]
	v_mfma_f32_16x16x32_bf16 v[80:83], v[176:179], v[200:203], v[80:83]
	v_mfma_f32_16x16x32_bf16 v[68:71], v[168:171], v[208:211], v[68:71]
	v_mfma_f32_16x16x32_bf16 v[64:67], v[176:179], v[208:211], v[64:67]
	v_mfma_f32_16x16x32_bf16 v[116:119], v[172:175], v[188:191], v[116:119]
	v_mfma_f32_16x16x32_bf16 v[112:115], v[180:183], v[188:191], v[112:115]
	v_mfma_f32_16x16x32_bf16 v[100:103], v[172:175], v[196:199], v[100:103]
	v_mfma_f32_16x16x32_bf16 v[96:99], v[180:183], v[196:199], v[96:99]
	v_mfma_f32_16x16x32_bf16 v[84:87], v[172:175], v[204:207], v[84:87]
	v_mfma_f32_16x16x32_bf16 v[80:83], v[180:183], v[204:207], v[80:83]
	v_mfma_f32_16x16x32_bf16 v[68:71], v[172:175], v[212:215], v[68:71]
	v_mfma_f32_16x16x32_bf16 v[64:67], v[180:183], v[212:215], v[64:67]
	s_setprio 0
	s_barrier
	s_add_i32 s54, s47, s3
	v_lshl_add_u64 v[216:217], s[34:35], 0, v[130:131]
	s_mov_b32 m0, s54
	ds_read_b128 v[184:187], v153 offset:16384
	ds_read_b128 v[188:191], v153 offset:17408
	ds_read_b128 v[192:195], v153 offset:18432
	ds_read_b128 v[196:199], v153 offset:19456
	ds_read_b128 v[200:203], v153 offset:20480
	ds_read_b128 v[204:207], v153 offset:21504
	ds_read_b128 v[208:211], v153 offset:22528
	ds_read_b128 v[212:215], v153 offset:23552
	global_load_lds_dwordx4 v[216:217], off
	s_add_i32 m0, s54, 0x2000
	s_add_u32 s54, s34, 0x40000
	v_lshl_add_u64 v[218:219], s[34:35], 0, v[134:135]
	s_addc_u32 s55, s35, 0
	s_add_i32 s56, s48, s3
	global_load_lds_dwordx4 v[218:219], off
	v_lshl_add_u64 v[222:223], s[54:55], 0, v[130:131]
	s_mov_b32 m0, s56
	v_lshl_add_u64 v[224:225], s[36:37], 0, v[132:133]
	global_load_lds_dwordx4 v[222:223], off
	v_lshl_add_u64 v[222:223], s[54:55], 0, v[134:135]
	s_add_i32 m0, s56, 0x2000
	s_nop 0
	global_load_lds_dwordx4 v[222:223], off
	v_lshl_add_u64 v[222:223], s[36:37], 0, v[128:129]
	s_mov_b32 m0, s33
	s_nop 0
	global_load_lds_dwordx4 v[222:223], off
	s_mov_b32 m0, s38
	s_nop 0
	global_load_lds_dwordx4 v[224:225], off
	s_waitcnt vmcnt(8)
	s_waitcnt lgkmcnt(0)
	s_barrier
	s_setprio 1
	s_waitcnt lgkmcnt(0)
	s_nop 0
	v_mfma_f32_16x16x32_bf16 v[60:63], v[144:147], v[184:187], v[60:63]
	v_mfma_f32_16x16x32_bf16 v[56:59], v[160:163], v[184:187], v[56:59]
	v_mfma_f32_16x16x32_bf16 v[44:47], v[144:147], v[192:195], v[44:47]
	v_mfma_f32_16x16x32_bf16 v[40:43], v[160:163], v[192:195], v[40:43]
	v_mfma_f32_16x16x32_bf16 v[28:31], v[144:147], v[200:203], v[28:31]
	v_mfma_f32_16x16x32_bf16 v[24:27], v[160:163], v[200:203], v[24:27]
	v_mfma_f32_16x16x32_bf16 v[12:15], v[144:147], v[208:211], v[12:15]
	v_mfma_f32_16x16x32_bf16 v[8:11], v[160:163], v[208:211], v[8:11]
	v_mfma_f32_16x16x32_bf16 v[60:63], v[156:159], v[188:191], v[60:63]
	v_mfma_f32_16x16x32_bf16 v[56:59], v[164:167], v[188:191], v[56:59]
	v_mfma_f32_16x16x32_bf16 v[44:47], v[156:159], v[196:199], v[44:47]
	v_mfma_f32_16x16x32_bf16 v[40:43], v[164:167], v[196:199], v[40:43]
	v_mfma_f32_16x16x32_bf16 v[28:31], v[156:159], v[204:207], v[28:31]
	v_mfma_f32_16x16x32_bf16 v[24:27], v[164:167], v[204:207], v[24:27]
	v_mfma_f32_16x16x32_bf16 v[12:15], v[156:159], v[212:215], v[12:15]
	v_mfma_f32_16x16x32_bf16 v[8:11], v[164:167], v[212:215], v[8:11]
	s_setprio 0
	s_setprio 1
	v_mfma_f32_16x16x32_bf16 v[52:55], v[168:171], v[184:187], v[52:55]
	v_mfma_f32_16x16x32_bf16 v[48:51], v[176:179], v[184:187], v[48:51]
	v_mfma_f32_16x16x32_bf16 v[36:39], v[168:171], v[192:195], v[36:39]
	v_mfma_f32_16x16x32_bf16 v[32:35], v[176:179], v[192:195], v[32:35]
	v_mfma_f32_16x16x32_bf16 v[20:23], v[168:171], v[200:203], v[20:23]
	v_mfma_f32_16x16x32_bf16 v[16:19], v[176:179], v[200:203], v[16:19]
	v_mfma_f32_16x16x32_bf16 v[4:7], v[168:171], v[208:211], v[4:7]
	v_mfma_f32_16x16x32_bf16 v[0:3], v[176:179], v[208:211], v[0:3]
	v_mfma_f32_16x16x32_bf16 v[52:55], v[172:175], v[188:191], v[52:55]
	v_mfma_f32_16x16x32_bf16 v[48:51], v[180:183], v[188:191], v[48:51]
	v_mfma_f32_16x16x32_bf16 v[36:39], v[172:175], v[196:199], v[36:39]
	v_mfma_f32_16x16x32_bf16 v[32:35], v[180:183], v[196:199], v[32:35]
	v_mfma_f32_16x16x32_bf16 v[20:23], v[172:175], v[204:207], v[20:23]
	v_mfma_f32_16x16x32_bf16 v[16:19], v[180:183], v[204:207], v[16:19]
	v_mfma_f32_16x16x32_bf16 v[4:7], v[172:175], v[212:215], v[4:7]
	v_mfma_f32_16x16x32_bf16 v[0:3], v[180:183], v[212:215], v[0:3]
	s_setprio 0
	s_barrier
	s_add_i32 s54, 0, 0x18000
	v_add_u32_e32 v155, s54, v149
	s_add_i32 s55, 0, 0x1c000
	ds_read_b128 v[144:147], v155
	ds_read_b128 v[156:159], v155 offset:1024
	ds_read_b128 v[160:163], v155 offset:2048
	ds_read_b128 v[164:167], v155 offset:3072
	v_add_u32_e32 v155, s55, v149
	ds_read_b128 v[168:171], v155
	ds_read_b128 v[172:175], v155 offset:1024
	ds_read_b128 v[176:179], v155 offset:2048
	ds_read_b128 v[180:183], v155 offset:3072
	s_add_u32 s36, s36, 0x40000
	s_addc_u32 s37, s37, 0
	s_mov_b32 m0, s39
	v_lshl_add_u64 v[226:227], s[36:37], 0, v[128:129]
	ds_read_b128 v[184:187], v153 offset:32768
	ds_read_b128 v[188:191], v153 offset:33792
	ds_read_b128 v[192:195], v153 offset:34816
	ds_read_b128 v[196:199], v153 offset:35840
	ds_read_b128 v[200:203], v153 offset:36864
	ds_read_b128 v[204:207], v153 offset:37888
	ds_read_b128 v[208:211], v153 offset:38912
	ds_read_b128 v[212:215], v153 offset:39936
	global_load_lds_dwordx4 v[226:227], off
	v_lshl_add_u64 v[226:227], s[36:37], 0, v[132:133]
	s_mov_b32 m0, s40
	s_nop 0
	global_load_lds_dwordx4 v[226:227], off
	s_waitcnt vmcnt(8)
	s_waitcnt lgkmcnt(0)
	s_barrier
	s_setprio 1
	s_waitcnt lgkmcnt(0)
	s_nop 0
	v_mfma_f32_16x16x32_bf16 v[124:127], v[144:147], v[184:187], v[124:127]
	v_mfma_f32_16x16x32_bf16 v[120:123], v[160:163], v[184:187], v[120:123]
	v_mfma_f32_16x16x32_bf16 v[108:111], v[144:147], v[192:195], v[108:111]
	v_mfma_f32_16x16x32_bf16 v[104:107], v[160:163], v[192:195], v[104:107]
	v_mfma_f32_16x16x32_bf16 v[92:95], v[144:147], v[200:203], v[92:95]
	v_mfma_f32_16x16x32_bf16 v[88:91], v[160:163], v[200:203], v[88:91]
	v_mfma_f32_16x16x32_bf16 v[76:79], v[144:147], v[208:211], v[76:79]
	v_mfma_f32_16x16x32_bf16 v[72:75], v[160:163], v[208:211], v[72:75]
	v_mfma_f32_16x16x32_bf16 v[124:127], v[156:159], v[188:191], v[124:127]
	v_mfma_f32_16x16x32_bf16 v[120:123], v[164:167], v[188:191], v[120:123]
	v_mfma_f32_16x16x32_bf16 v[108:111], v[156:159], v[196:199], v[108:111]
	v_mfma_f32_16x16x32_bf16 v[104:107], v[164:167], v[196:199], v[104:107]
	v_mfma_f32_16x16x32_bf16 v[92:95], v[156:159], v[204:207], v[92:95]
	v_mfma_f32_16x16x32_bf16 v[88:91], v[164:167], v[204:207], v[88:91]
	v_mfma_f32_16x16x32_bf16 v[76:79], v[156:159], v[212:215], v[76:79]
	v_mfma_f32_16x16x32_bf16 v[72:75], v[164:167], v[212:215], v[72:75]
	s_setprio 0
	s_setprio 1
	v_mfma_f32_16x16x32_bf16 v[116:119], v[168:171], v[184:187], v[116:119]
	v_mfma_f32_16x16x32_bf16 v[112:115], v[176:179], v[184:187], v[112:115]
	v_mfma_f32_16x16x32_bf16 v[100:103], v[168:171], v[192:195], v[100:103]
	v_mfma_f32_16x16x32_bf16 v[96:99], v[176:179], v[192:195], v[96:99]
	v_mfma_f32_16x16x32_bf16 v[84:87], v[168:171], v[200:203], v[84:87]
	v_mfma_f32_16x16x32_bf16 v[80:83], v[176:179], v[200:203], v[80:83]
	v_mfma_f32_16x16x32_bf16 v[68:71], v[168:171], v[208:211], v[68:71]
	v_mfma_f32_16x16x32_bf16 v[64:67], v[176:179], v[208:211], v[64:67]
	v_mfma_f32_16x16x32_bf16 v[116:119], v[172:175], v[188:191], v[116:119]
	v_mfma_f32_16x16x32_bf16 v[112:115], v[180:183], v[188:191], v[112:115]
	v_mfma_f32_16x16x32_bf16 v[100:103], v[172:175], v[196:199], v[100:103]
	v_mfma_f32_16x16x32_bf16 v[96:99], v[180:183], v[196:199], v[96:99]
	v_mfma_f32_16x16x32_bf16 v[84:87], v[172:175], v[204:207], v[84:87]
	v_mfma_f32_16x16x32_bf16 v[80:83], v[180:183], v[204:207], v[80:83]
	v_mfma_f32_16x16x32_bf16 v[68:71], v[172:175], v[212:215], v[68:71]
	v_mfma_f32_16x16x32_bf16 v[64:67], v[180:183], v[212:215], v[64:67]
	s_setprio 0
	s_barrier
	s_add_i32 s36, s54, s3
	v_lshl_add_u64 v[216:217], v[216:217], 0, s[16:17]
	s_mov_b32 m0, s36
	ds_read_b128 v[184:187], v153 offset:49152
	ds_read_b128 v[188:191], v153 offset:50176
	ds_read_b128 v[192:195], v153 offset:51200
	ds_read_b128 v[196:199], v153 offset:52224
	ds_read_b128 v[200:203], v153 offset:53248
	ds_read_b128 v[204:207], v153 offset:54272
	ds_read_b128 v[208:211], v153 offset:55296
	ds_read_b128 v[212:215], v153 offset:56320
	global_load_lds_dwordx4 v[216:217], off
	s_add_i32 m0, s36, 0x2000
	s_add_u32 s34, s34, 0x40080
	v_lshl_add_u64 v[216:217], v[218:219], 0, s[16:17]
	s_addc_u32 s35, s35, 0
	s_add_i32 s36, s55, s3
	global_load_lds_dwordx4 v[216:217], off
	v_lshl_add_u64 v[216:217], s[34:35], 0, v[130:131]
	s_mov_b32 m0, s36
	s_nop 0
	global_load_lds_dwordx4 v[216:217], off
	v_lshl_add_u64 v[216:217], s[34:35], 0, v[134:135]
	s_add_i32 m0, s36, 0x2000
	s_nop 0
	global_load_lds_dwordx4 v[216:217], off
	v_lshl_add_u64 v[216:217], v[222:223], 0, s[16:17]
	s_mov_b32 m0, s44
	s_nop 0
	global_load_lds_dwordx4 v[216:217], off
	v_lshl_add_u64 v[216:217], v[224:225], 0, s[16:17]
	s_mov_b32 m0, s45
	s_nop 0
	global_load_lds_dwordx4 v[216:217], off
	s_waitcnt vmcnt(8)
	s_waitcnt lgkmcnt(0)
	s_barrier
	s_setprio 1
	s_waitcnt lgkmcnt(0)
	v_mfma_f32_16x16x32_bf16 v[60:63], v[144:147], v[184:187], v[60:63]
	v_mfma_f32_16x16x32_bf16 v[56:59], v[160:163], v[184:187], v[56:59]
	v_mfma_f32_16x16x32_bf16 v[44:47], v[144:147], v[192:195], v[44:47]
	v_mfma_f32_16x16x32_bf16 v[40:43], v[160:163], v[192:195], v[40:43]
	v_mfma_f32_16x16x32_bf16 v[28:31], v[144:147], v[200:203], v[28:31]
	v_mfma_f32_16x16x32_bf16 v[24:27], v[160:163], v[200:203], v[24:27]
	v_mfma_f32_16x16x32_bf16 v[12:15], v[144:147], v[208:211], v[12:15]
	v_mfma_f32_16x16x32_bf16 v[8:11], v[160:163], v[208:211], v[8:11]
	v_mfma_f32_16x16x32_bf16 v[60:63], v[156:159], v[188:191], v[60:63]
	v_mfma_f32_16x16x32_bf16 v[56:59], v[164:167], v[188:191], v[56:59]
	v_mfma_f32_16x16x32_bf16 v[44:47], v[156:159], v[196:199], v[44:47]
	v_mfma_f32_16x16x32_bf16 v[40:43], v[164:167], v[196:199], v[40:43]
	v_mfma_f32_16x16x32_bf16 v[28:31], v[156:159], v[204:207], v[28:31]
	v_mfma_f32_16x16x32_bf16 v[24:27], v[164:167], v[204:207], v[24:27]
	v_mfma_f32_16x16x32_bf16 v[12:15], v[156:159], v[212:215], v[12:15]
	v_mfma_f32_16x16x32_bf16 v[8:11], v[164:167], v[212:215], v[8:11]
	s_setprio 0
	s_setprio 1
	v_mfma_f32_16x16x32_bf16 v[52:55], v[168:171], v[184:187], v[52:55]
	v_mfma_f32_16x16x32_bf16 v[48:51], v[176:179], v[184:187], v[48:51]
	v_mfma_f32_16x16x32_bf16 v[36:39], v[168:171], v[192:195], v[36:39]
	v_mfma_f32_16x16x32_bf16 v[32:35], v[176:179], v[192:195], v[32:35]
	v_mfma_f32_16x16x32_bf16 v[20:23], v[168:171], v[200:203], v[20:23]
	v_mfma_f32_16x16x32_bf16 v[16:19], v[176:179], v[200:203], v[16:19]
	v_mfma_f32_16x16x32_bf16 v[4:7], v[168:171], v[208:211], v[4:7]
	v_mfma_f32_16x16x32_bf16 v[0:3], v[176:179], v[208:211], v[0:3]
	v_mfma_f32_16x16x32_bf16 v[52:55], v[172:175], v[188:191], v[52:55]
	v_mfma_f32_16x16x32_bf16 v[48:51], v[180:183], v[188:191], v[48:51]
	v_mfma_f32_16x16x32_bf16 v[36:39], v[172:175], v[196:199], v[36:39]
	v_mfma_f32_16x16x32_bf16 v[32:35], v[180:183], v[196:199], v[32:35]
	v_mfma_f32_16x16x32_bf16 v[20:23], v[172:175], v[204:207], v[20:23]
	v_mfma_f32_16x16x32_bf16 v[16:19], v[180:183], v[204:207], v[16:19]
	v_mfma_f32_16x16x32_bf16 v[4:7], v[172:175], v[212:215], v[4:7]
	v_mfma_f32_16x16x32_bf16 v[0:3], v[180:183], v[212:215], v[0:3]
	s_setprio 0
	s_barrier
	s_add_i32 s53, s53, 2
	s_add_u32 s30, s30, 0x100
	s_addc_u32 s31, s31, 0
	s_add_u32 s51, s51, 0x100
	s_addc_u32 s52, s52, 0
	s_cmp_gt_u32 s53, 13
	s_cbranch_scc0 .LBB0_726
	s_and_b64 vcc, exec, s[18:19]
	s_cbranch_vccz .LBB0_729
	s_barrier

.Ldhs8_done:
	ds_read_b128 v[150:153], v147
	ds_read_b128 v[154:157], v147 offset:1024
	ds_read_b128 v[158:161], v147 offset:2048
	ds_read_b128 v[162:165], v147 offset:3072
	ds_read_b128 v[166:169], v148
	ds_read_b128 v[170:173], v148 offset:1024
	ds_read_b128 v[174:177], v148 offset:2048
	ds_read_b128 v[178:181], v148 offset:3072
	s_add_u32 s38, s36, 0xfffc0080
	s_addc_u32 s39, s37, -1
	s_cmp_eq_u32 s61, 12
	s_cselect_b32 s41, s27, s39
	s_cselect_b32 s40, s57, s38
	s_cselect_b32 s39, s25, s60
	s_cselect_b32 s38, s58, s59
	v_lshl_add_u64 v[214:215], s[36:37], 0, v[136:137]
	s_add_i32 m0, s35, 0xc000
	ds_read_b128 v[182:185], v149
	ds_read_b128 v[186:189], v149 offset:1024
	ds_read_b128 v[190:193], v149 offset:2048
	ds_read_b128 v[194:197], v149 offset:3072
	ds_read_b128 v[198:201], v149 offset:4096
	ds_read_b128 v[202:205], v149 offset:5120
	ds_read_b128 v[206:209], v149 offset:6144
	ds_read_b128 v[210:213], v149 offset:7168
	global_load_lds_dwordx4 v[214:215], off
	v_lshl_add_u64 v[214:215], s[36:37], 0, v[138:139]
	s_add_i32 m0, s35, 0xe000
	s_nop 0
	global_load_lds_dwordx4 v[214:215], off
	s_waitcnt vmcnt(9)
	s_waitcnt lgkmcnt(0)
	s_barrier
	s_setprio 1
	s_waitcnt lgkmcnt(0)
	v_mfma_f32_16x16x32_bf16 v[124:127], v[150:153], v[182:185], v[124:127]
	v_mfma_f32_16x16x32_bf16 v[120:123], v[158:161], v[182:185], v[120:123]
	v_mfma_f32_16x16x32_bf16 v[108:111], v[150:153], v[190:193], v[108:111]
	v_mfma_f32_16x16x32_bf16 v[104:107], v[158:161], v[190:193], v[104:107]
	v_mfma_f32_16x16x32_bf16 v[92:95], v[150:153], v[198:201], v[92:95]
	v_mfma_f32_16x16x32_bf16 v[88:91], v[158:161], v[198:201], v[88:91]
	v_mfma_f32_16x16x32_bf16 v[76:79], v[150:153], v[206:209], v[76:79]
	v_mfma_f32_16x16x32_bf16 v[72:75], v[158:161], v[206:209], v[72:75]
	v_mfma_f32_16x16x32_bf16 v[124:127], v[154:157], v[186:189], v[124:127]
	v_mfma_f32_16x16x32_bf16 v[120:123], v[162:165], v[186:189], v[120:123]
	v_mfma_f32_16x16x32_bf16 v[108:111], v[154:157], v[194:197], v[108:111]
	v_mfma_f32_16x16x32_bf16 v[104:107], v[162:165], v[194:197], v[104:107]
	v_mfma_f32_16x16x32_bf16 v[92:95], v[154:157], v[202:205], v[92:95]
	v_mfma_f32_16x16x32_bf16 v[88:91], v[162:165], v[202:205], v[88:91]
	v_mfma_f32_16x16x32_bf16 v[76:79], v[154:157], v[210:213], v[76:79]
	v_mfma_f32_16x16x32_bf16 v[72:75], v[162:165], v[210:213], v[72:75]
	s_setprio 0
	s_setprio 1
	v_mfma_f32_16x16x32_bf16 v[116:119], v[166:169], v[182:185], v[116:119]
	v_mfma_f32_16x16x32_bf16 v[112:115], v[174:177], v[182:185], v[112:115]
	v_mfma_f32_16x16x32_bf16 v[100:103], v[166:169], v[190:193], v[100:103]
	v_mfma_f32_16x16x32_bf16 v[96:99], v[174:177], v[190:193], v[96:99]
	v_mfma_f32_16x16x32_bf16 v[84:87], v[166:169], v[198:201], v[84:87]
	v_mfma_f32_16x16x32_bf16 v[80:83], v[174:177], v[198:201], v[80:83]
	v_mfma_f32_16x16x32_bf16 v[68:71], v[166:169], v[206:209], v[68:71]
	v_mfma_f32_16x16x32_bf16 v[64:67], v[174:177], v[206:209], v[64:67]
	v_mfma_f32_16x16x32_bf16 v[116:119], v[170:173], v[186:189], v[116:119]
	v_mfma_f32_16x16x32_bf16 v[112:115], v[178:181], v[186:189], v[112:115]
	v_mfma_f32_16x16x32_bf16 v[100:103], v[170:173], v[194:197], v[100:103]
	v_mfma_f32_16x16x32_bf16 v[96:99], v[178:181], v[194:197], v[96:99]
	v_mfma_f32_16x16x32_bf16 v[84:87], v[170:173], v[202:205], v[84:87]
	v_mfma_f32_16x16x32_bf16 v[80:83], v[178:181], v[202:205], v[80:83]
	v_mfma_f32_16x16x32_bf16 v[68:71], v[170:173], v[210:213], v[68:71]
	v_mfma_f32_16x16x32_bf16 v[64:67], v[178:181], v[210:213], v[64:67]
	s_setprio 0
	s_barrier
	s_add_i32 s62, s50, s3
	v_lshl_add_u64 v[214:215], s[38:39], 0, v[130:131]
	s_mov_b32 m0, s62
	ds_read_b128 v[182:185], v149 offset:16384
	ds_read_b128 v[186:189], v149 offset:17408
	ds_read_b128 v[190:193], v149 offset:18432
	ds_read_b128 v[194:197], v149 offset:19456
	ds_read_b128 v[198:201], v149 offset:20480
	ds_read_b128 v[202:205], v149 offset:21504
	ds_read_b128 v[206:209], v149 offset:22528
	ds_read_b128 v[210:213], v149 offset:23552
	global_load_lds_dwordx4 v[214:215], off
	s_add_i32 m0, s62, 0x2000
	s_add_u32 s62, s38, 0x40000
	v_lshl_add_u64 v[216:217], s[38:39], 0, v[134:135]
	s_addc_u32 s63, s39, 0
	s_add_i32 s64, s51, s3
	global_load_lds_dwordx4 v[216:217], off
	v_lshl_add_u64 v[218:219], s[62:63], 0, v[130:131]
	s_mov_b32 m0, s64
	v_lshl_add_u64 v[222:223], s[40:41], 0, v[132:133]
	global_load_lds_dwordx4 v[218:219], off
	v_lshl_add_u64 v[218:219], s[62:63], 0, v[134:135]
	s_add_i32 m0, s64, 0x2000
	s_nop 0
	global_load_lds_dwordx4 v[218:219], off
	v_lshl_add_u64 v[218:219], s[40:41], 0, v[128:129]
	s_mov_b32 m0, s35
	s_nop 0
	global_load_lds_dwordx4 v[218:219], off
	s_mov_b32 m0, s42
	s_nop 0
	global_load_lds_dwordx4 v[222:223], off
	s_waitcnt vmcnt(9)
	s_waitcnt lgkmcnt(0)
	s_barrier
	s_setprio 1
	s_waitcnt lgkmcnt(0)
	s_nop 0
	v_mfma_f32_16x16x32_bf16 v[60:63], v[150:153], v[182:185], v[60:63]
	v_mfma_f32_16x16x32_bf16 v[56:59], v[158:161], v[182:185], v[56:59]
	v_mfma_f32_16x16x32_bf16 v[44:47], v[150:153], v[190:193], v[44:47]
	v_mfma_f32_16x16x32_bf16 v[40:43], v[158:161], v[190:193], v[40:43]
	v_mfma_f32_16x16x32_bf16 v[28:31], v[150:153], v[198:201], v[28:31]
	v_mfma_f32_16x16x32_bf16 v[24:27], v[158:161], v[198:201], v[24:27]
	v_mfma_f32_16x16x32_bf16 v[12:15], v[150:153], v[206:209], v[12:15]
	v_mfma_f32_16x16x32_bf16 v[8:11], v[158:161], v[206:209], v[8:11]
	v_mfma_f32_16x16x32_bf16 v[60:63], v[154:157], v[186:189], v[60:63]
	v_mfma_f32_16x16x32_bf16 v[56:59], v[162:165], v[186:189], v[56:59]
	v_mfma_f32_16x16x32_bf16 v[44:47], v[154:157], v[194:197], v[44:47]
	v_mfma_f32_16x16x32_bf16 v[40:43], v[162:165], v[194:197], v[40:43]
	v_mfma_f32_16x16x32_bf16 v[28:31], v[154:157], v[202:205], v[28:31]
	v_mfma_f32_16x16x32_bf16 v[24:27], v[162:165], v[202:205], v[24:27]
	v_mfma_f32_16x16x32_bf16 v[12:15], v[154:157], v[210:213], v[12:15]
	v_mfma_f32_16x16x32_bf16 v[8:11], v[162:165], v[210:213], v[8:11]
	s_setprio 0
	s_setprio 1
	v_mfma_f32_16x16x32_bf16 v[52:55], v[166:169], v[182:185], v[52:55]
	v_mfma_f32_16x16x32_bf16 v[48:51], v[174:177], v[182:185], v[48:51]
	v_mfma_f32_16x16x32_bf16 v[36:39], v[166:169], v[190:193], v[36:39]
	v_mfma_f32_16x16x32_bf16 v[32:35], v[174:177], v[190:193], v[32:35]
	v_mfma_f32_16x16x32_bf16 v[20:23], v[166:169], v[198:201], v[20:23]
	v_mfma_f32_16x16x32_bf16 v[16:19], v[174:177], v[198:201], v[16:19]
	v_mfma_f32_16x16x32_bf16 v[4:7], v[166:169], v[206:209], v[4:7]
	v_mfma_f32_16x16x32_bf16 v[0:3], v[174:177], v[206:209], v[0:3]
	v_mfma_f32_16x16x32_bf16 v[52:55], v[170:173], v[186:189], v[52:55]
	v_mfma_f32_16x16x32_bf16 v[48:51], v[178:181], v[186:189], v[48:51]
	v_mfma_f32_16x16x32_bf16 v[36:39], v[170:173], v[194:197], v[36:39]
	v_mfma_f32_16x16x32_bf16 v[32:35], v[178:181], v[194:197], v[32:35]
	v_mfma_f32_16x16x32_bf16 v[20:23], v[170:173], v[202:205], v[20:23]
	v_mfma_f32_16x16x32_bf16 v[16:19], v[178:181], v[202:205], v[16:19]
	v_mfma_f32_16x16x32_bf16 v[4:7], v[170:173], v[210:213], v[4:7]
	v_mfma_f32_16x16x32_bf16 v[0:3], v[178:181], v[210:213], v[0:3]
	s_setprio 0
	s_barrier
	s_add_i32 s62, 0, 0x18000
	s_add_i32 s63, 0, 0x1c000
	v_add_u32_e32 v162, s62, v145
	v_add_u32_e32 v178, s63, v145
	ds_read_b128 v[150:153], v162
	ds_read_b128 v[154:157], v162 offset:1024
	ds_read_b128 v[158:161], v162 offset:2048
	ds_read_b128 v[162:165], v162 offset:3072
	ds_read_b128 v[166:169], v178
	ds_read_b128 v[170:173], v178 offset:1024
	ds_read_b128 v[174:177], v178 offset:2048
	ds_read_b128 v[178:181], v178 offset:3072
	s_add_u32 s40, s40, 0x40000
	s_addc_u32 s41, s41, 0
	s_mov_b32 m0, s43
	v_lshl_add_u64 v[224:225], s[40:41], 0, v[128:129]
	ds_read_b128 v[182:185], v149 offset:32768
	ds_read_b128 v[186:189], v149 offset:33792
	ds_read_b128 v[190:193], v149 offset:34816
	ds_read_b128 v[194:197], v149 offset:35840
	ds_read_b128 v[198:201], v149 offset:36864
	ds_read_b128 v[202:205], v149 offset:37888
	ds_read_b128 v[206:209], v149 offset:38912
	ds_read_b128 v[210:213], v149 offset:39936
	global_load_lds_dwordx4 v[224:225], off
	v_lshl_add_u64 v[224:225], s[40:41], 0, v[132:133]
	s_mov_b32 m0, s44
	s_nop 0
	global_load_lds_dwordx4 v[224:225], off
	s_waitcnt vmcnt(8)
	s_waitcnt lgkmcnt(0)
	s_barrier
	s_setprio 1
	s_waitcnt lgkmcnt(0)
	s_nop 0
	v_mfma_f32_16x16x32_bf16 v[124:127], v[150:153], v[182:185], v[124:127]
	v_mfma_f32_16x16x32_bf16 v[120:123], v[158:161], v[182:185], v[120:123]
	v_mfma_f32_16x16x32_bf16 v[108:111], v[150:153], v[190:193], v[108:111]
	v_mfma_f32_16x16x32_bf16 v[104:107], v[158:161], v[190:193], v[104:107]
	v_mfma_f32_16x16x32_bf16 v[92:95], v[150:153], v[198:201], v[92:95]
	v_mfma_f32_16x16x32_bf16 v[88:91], v[158:161], v[198:201], v[88:91]
	v_mfma_f32_16x16x32_bf16 v[76:79], v[150:153], v[206:209], v[76:79]
	v_mfma_f32_16x16x32_bf16 v[72:75], v[158:161], v[206:209], v[72:75]
	v_mfma_f32_16x16x32_bf16 v[124:127], v[154:157], v[186:189], v[124:127]
	v_mfma_f32_16x16x32_bf16 v[120:123], v[162:165], v[186:189], v[120:123]
	v_mfma_f32_16x16x32_bf16 v[108:111], v[154:157], v[194:197], v[108:111]
	v_mfma_f32_16x16x32_bf16 v[104:107], v[162:165], v[194:197], v[104:107]
	v_mfma_f32_16x16x32_bf16 v[92:95], v[154:157], v[202:205], v[92:95]
	v_mfma_f32_16x16x32_bf16 v[88:91], v[162:165], v[202:205], v[88:91]
	v_mfma_f32_16x16x32_bf16 v[76:79], v[154:157], v[210:213], v[76:79]
	v_mfma_f32_16x16x32_bf16 v[72:75], v[162:165], v[210:213], v[72:75]
	s_setprio 0
	s_setprio 1
	v_mfma_f32_16x16x32_bf16 v[116:119], v[166:169], v[182:185], v[116:119]
	v_mfma_f32_16x16x32_bf16 v[112:115], v[174:177], v[182:185], v[112:115]
	v_mfma_f32_16x16x32_bf16 v[100:103], v[166:169], v[190:193], v[100:103]
	v_mfma_f32_16x16x32_bf16 v[96:99], v[174:177], v[190:193], v[96:99]
	v_mfma_f32_16x16x32_bf16 v[84:87], v[166:169], v[198:201], v[84:87]
	v_mfma_f32_16x16x32_bf16 v[80:83], v[174:177], v[198:201], v[80:83]
	v_mfma_f32_16x16x32_bf16 v[68:71], v[166:169], v[206:209], v[68:71]
	v_mfma_f32_16x16x32_bf16 v[64:67], v[174:177], v[206:209], v[64:67]
	v_mfma_f32_16x16x32_bf16 v[116:119], v[170:173], v[186:189], v[116:119]
	v_mfma_f32_16x16x32_bf16 v[112:115], v[178:181], v[186:189], v[112:115]
	v_mfma_f32_16x16x32_bf16 v[100:103], v[170:173], v[194:197], v[100:103]
	v_mfma_f32_16x16x32_bf16 v[96:99], v[178:181], v[194:197], v[96:99]
	v_mfma_f32_16x16x32_bf16 v[84:87], v[170:173], v[202:205], v[84:87]
	v_mfma_f32_16x16x32_bf16 v[80:83], v[178:181], v[202:205], v[80:83]
	v_mfma_f32_16x16x32_bf16 v[68:71], v[170:173], v[210:213], v[68:71]
	v_mfma_f32_16x16x32_bf16 v[64:67], v[178:181], v[210:213], v[64:67]
	s_setprio 0
	s_barrier
	s_add_i32 s40, s62, s3
	v_lshl_add_u64 v[214:215], v[214:215], 0, s[12:13]
	s_mov_b32 m0, s40
	ds_read_b128 v[182:185], v149 offset:49152
	ds_read_b128 v[186:189], v149 offset:50176
	ds_read_b128 v[190:193], v149 offset:51200
	ds_read_b128 v[194:197], v149 offset:52224
	ds_read_b128 v[198:201], v149 offset:53248
	ds_read_b128 v[202:205], v149 offset:54272
	ds_read_b128 v[206:209], v149 offset:55296
	ds_read_b128 v[210:213], v149 offset:56320
	global_load_lds_dwordx4 v[214:215], off
	s_add_i32 m0, s40, 0x2000
	s_add_u32 s38, s38, 0x40080
	v_lshl_add_u64 v[214:215], v[216:217], 0, s[12:13]
	s_addc_u32 s39, s39, 0
	s_add_i32 s40, s63, s3
	global_load_lds_dwordx4 v[214:215], off
	v_lshl_add_u64 v[214:215], s[38:39], 0, v[130:131]
	s_mov_b32 m0, s40
	s_nop 0
	global_load_lds_dwordx4 v[214:215], off
	v_lshl_add_u64 v[214:215], s[38:39], 0, v[134:135]
	s_add_i32 m0, s40, 0x2000
	s_nop 0
	global_load_lds_dwordx4 v[214:215], off
	v_lshl_add_u64 v[214:215], v[218:219], 0, s[12:13]
	s_mov_b32 m0, s47
	s_nop 0
	global_load_lds_dwordx4 v[214:215], off
	v_lshl_add_u64 v[214:215], v[222:223], 0, s[12:13]
	s_mov_b32 m0, s48
	s_nop 0
	global_load_lds_dwordx4 v[214:215], off
	s_waitcnt vmcnt(8)
	s_waitcnt lgkmcnt(0)
	s_barrier
	s_setprio 1
	s_waitcnt lgkmcnt(0)
	v_mfma_f32_16x16x32_bf16 v[60:63], v[150:153], v[182:185], v[60:63]
	v_mfma_f32_16x16x32_bf16 v[56:59], v[158:161], v[182:185], v[56:59]
	v_mfma_f32_16x16x32_bf16 v[44:47], v[150:153], v[190:193], v[44:47]
	v_mfma_f32_16x16x32_bf16 v[40:43], v[158:161], v[190:193], v[40:43]
	v_mfma_f32_16x16x32_bf16 v[28:31], v[150:153], v[198:201], v[28:31]
	v_mfma_f32_16x16x32_bf16 v[24:27], v[158:161], v[198:201], v[24:27]
	v_mfma_f32_16x16x32_bf16 v[12:15], v[150:153], v[206:209], v[12:15]
	v_mfma_f32_16x16x32_bf16 v[8:11], v[158:161], v[206:209], v[8:11]
	v_mfma_f32_16x16x32_bf16 v[60:63], v[154:157], v[186:189], v[60:63]
	v_mfma_f32_16x16x32_bf16 v[56:59], v[162:165], v[186:189], v[56:59]
	v_mfma_f32_16x16x32_bf16 v[44:47], v[154:157], v[194:197], v[44:47]
	v_mfma_f32_16x16x32_bf16 v[40:43], v[162:165], v[194:197], v[40:43]
	v_mfma_f32_16x16x32_bf16 v[28:31], v[154:157], v[202:205], v[28:31]
	v_mfma_f32_16x16x32_bf16 v[24:27], v[162:165], v[202:205], v[24:27]
	v_mfma_f32_16x16x32_bf16 v[12:15], v[154:157], v[210:213], v[12:15]
	v_mfma_f32_16x16x32_bf16 v[8:11], v[162:165], v[210:213], v[8:11]
	s_setprio 0
	s_setprio 1
	v_mfma_f32_16x16x32_bf16 v[52:55], v[166:169], v[182:185], v[52:55]
	v_mfma_f32_16x16x32_bf16 v[48:51], v[174:177], v[182:185], v[48:51]
	v_mfma_f32_16x16x32_bf16 v[36:39], v[166:169], v[190:193], v[36:39]
	v_mfma_f32_16x16x32_bf16 v[32:35], v[174:177], v[190:193], v[32:35]
	v_mfma_f32_16x16x32_bf16 v[20:23], v[166:169], v[198:201], v[20:23]
	v_mfma_f32_16x16x32_bf16 v[16:19], v[174:177], v[198:201], v[16:19]
	v_mfma_f32_16x16x32_bf16 v[4:7], v[166:169], v[206:209], v[4:7]
	v_mfma_f32_16x16x32_bf16 v[0:3], v[174:177], v[206:209], v[0:3]
	v_mfma_f32_16x16x32_bf16 v[52:55], v[170:173], v[186:189], v[52:55]
	v_mfma_f32_16x16x32_bf16 v[48:51], v[178:181], v[186:189], v[48:51]
	v_mfma_f32_16x16x32_bf16 v[36:39], v[170:173], v[194:197], v[36:39]
	v_mfma_f32_16x16x32_bf16 v[32:35], v[178:181], v[194:197], v[32:35]
	v_mfma_f32_16x16x32_bf16 v[20:23], v[170:173], v[202:205], v[20:23]
	v_mfma_f32_16x16x32_bf16 v[16:19], v[178:181], v[202:205], v[16:19]
	v_mfma_f32_16x16x32_bf16 v[4:7], v[170:173], v[210:213], v[4:7]
	v_mfma_f32_16x16x32_bf16 v[0:3], v[178:181], v[210:213], v[0:3]
	s_setprio 0
	s_barrier
	s_add_i32 s61, s61, 2
	s_add_u32 s36, s36, 0x100
	s_addc_u32 s37, s37, 0
	s_add_u32 s59, s59, 0x100
	s_addc_u32 s60, s60, 0
	s_cmp_gt_u32 s61, 13
	s_cbranch_scc0 .LBB0_877
	s_and_b64 vcc, exec, s[14:15]
	s_cbranch_vccz .LBB0_880
	s_barrier

.LBB0_954:
	ds_read_b128 v[144:147], v151
	ds_read_b128 v[156:159], v151 offset:1024
	ds_read_b128 v[160:163], v151 offset:2048
	ds_read_b128 v[164:167], v151 offset:3072
	ds_read_b128 v[168:171], v152
	ds_read_b128 v[172:175], v152 offset:1024
	ds_read_b128 v[176:179], v152 offset:2048
	ds_read_b128 v[180:183], v152 offset:3072
	s_add_u32 s36, s34, 0x3fe000
	s_addc_u32 s37, s35, 0
	s_cmp_eq_u32 s55, 60
	s_cselect_b32 s39, s25, s37
	s_cselect_b32 s38, s31, s36
	s_cselect_b32 s37, s23, s54
	s_cselect_b32 s36, s52, s53
	v_lshl_add_u64 v[216:217], s[34:35], 0, v[136:137]
	s_add_i32 m0, s33, 0xc000
	ds_read_b128 v[184:187], v153
	ds_read_b128 v[188:191], v153 offset:1024
	ds_read_b128 v[192:195], v153 offset:2048
	ds_read_b128 v[196:199], v153 offset:3072
	ds_read_b128 v[200:203], v153 offset:4096
	ds_read_b128 v[204:207], v153 offset:5120
	ds_read_b128 v[208:211], v153 offset:6144
	ds_read_b128 v[212:215], v153 offset:7168
	global_load_lds_dwordx4 v[216:217], off
	v_lshl_add_u64 v[216:217], s[34:35], 0, v[138:139]
	s_add_i32 m0, s33, 0xe000
	s_nop 0
	global_load_lds_dwordx4 v[216:217], off
	s_waitcnt vmcnt(8)
	s_waitcnt lgkmcnt(0)
	s_barrier
	s_setprio 1
	s_waitcnt lgkmcnt(0)
	s_nop 0
	v_mfma_f32_16x16x32_bf16 v[124:127], v[144:147], v[184:187], v[124:127]
	v_mfma_f32_16x16x32_bf16 v[120:123], v[160:163], v[184:187], v[120:123]
	v_mfma_f32_16x16x32_bf16 v[108:111], v[144:147], v[192:195], v[108:111]
	v_mfma_f32_16x16x32_bf16 v[104:107], v[160:163], v[192:195], v[104:107]
	v_mfma_f32_16x16x32_bf16 v[92:95], v[144:147], v[200:203], v[92:95]
	v_mfma_f32_16x16x32_bf16 v[88:91], v[160:163], v[200:203], v[88:91]
	v_mfma_f32_16x16x32_bf16 v[76:79], v[144:147], v[208:211], v[76:79]
	v_mfma_f32_16x16x32_bf16 v[72:75], v[160:163], v[208:211], v[72:75]
	v_mfma_f32_16x16x32_bf16 v[124:127], v[156:159], v[188:191], v[124:127]
	v_mfma_f32_16x16x32_bf16 v[120:123], v[164:167], v[188:191], v[120:123]
	v_mfma_f32_16x16x32_bf16 v[108:111], v[156:159], v[196:199], v[108:111]
	v_mfma_f32_16x16x32_bf16 v[104:107], v[164:167], v[196:199], v[104:107]
	v_mfma_f32_16x16x32_bf16 v[92:95], v[156:159], v[204:207], v[92:95]
	v_mfma_f32_16x16x32_bf16 v[88:91], v[164:167], v[204:207], v[88:91]
	v_mfma_f32_16x16x32_bf16 v[76:79], v[156:159], v[212:215], v[76:79]
	v_mfma_f32_16x16x32_bf16 v[72:75], v[164:167], v[212:215], v[72:75]
	s_setprio 0
	s_setprio 1
	v_mfma_f32_16x16x32_bf16 v[116:119], v[168:171], v[184:187], v[116:119]
	v_mfma_f32_16x16x32_bf16 v[112:115], v[176:179], v[184:187], v[112:115]
	v_mfma_f32_16x16x32_bf16 v[100:103], v[168:171], v[192:195], v[100:103]
	v_mfma_f32_16x16x32_bf16 v[96:99], v[176:179], v[192:195], v[96:99]
	v_mfma_f32_16x16x32_bf16 v[84:87], v[168:171], v[200:203], v[84:87]
	v_mfma_f32_16x16x32_bf16 v[80:83], v[176:179], v[200:203], v[80:83]
	v_mfma_f32_16x16x32_bf16 v[68:71], v[168:171], v[208:211], v[68:71]
	v_mfma_f32_16x16x32_bf16 v[64:67], v[176:179], v[208:211], v[64:67]
	v_mfma_f32_16x16x32_bf16 v[116:119], v[172:175], v[188:191], v[116:119]
	v_mfma_f32_16x16x32_bf16 v[112:115], v[180:183], v[188:191], v[112:115]
	v_mfma_f32_16x16x32_bf16 v[100:103], v[172:175], v[196:199], v[100:103]
	v_mfma_f32_16x16x32_bf16 v[96:99], v[180:183], v[196:199], v[96:99]
	v_mfma_f32_16x16x32_bf16 v[84:87], v[172:175], v[204:207], v[84:87]
	v_mfma_f32_16x16x32_bf16 v[80:83], v[180:183], v[204:207], v[80:83]
	v_mfma_f32_16x16x32_bf16 v[68:71], v[172:175], v[212:215], v[68:71]
	v_mfma_f32_16x16x32_bf16 v[64:67], v[180:183], v[212:215], v[64:67]
	s_setprio 0
	s_barrier
	s_add_i32 s56, s49, s3
	v_lshl_add_u64 v[216:217], s[36:37], 0, v[130:131]
	s_mov_b32 m0, s56
	ds_read_b128 v[184:187], v153 offset:16384
	ds_read_b128 v[188:191], v153 offset:17408
	ds_read_b128 v[192:195], v153 offset:18432
	ds_read_b128 v[196:199], v153 offset:19456
	ds_read_b128 v[200:203], v153 offset:20480
	ds_read_b128 v[204:207], v153 offset:21504
	ds_read_b128 v[208:211], v153 offset:22528
	ds_read_b128 v[212:215], v153 offset:23552
	global_load_lds_dwordx4 v[216:217], off
	s_add_i32 m0, s56, 0x2000
	s_add_u32 s56, s36, 0x100000
	v_lshl_add_u64 v[218:219], s[36:37], 0, v[134:135]
	s_addc_u32 s57, s37, 0
	s_add_i32 s58, s50, s3
	global_load_lds_dwordx4 v[218:219], off
	v_lshl_add_u64 v[222:223], s[56:57], 0, v[130:131]
	s_mov_b32 m0, s58
	v_lshl_add_u64 v[224:225], s[38:39], 0, v[132:133]
	global_load_lds_dwordx4 v[222:223], off
	v_lshl_add_u64 v[222:223], s[56:57], 0, v[134:135]
	s_add_i32 m0, s58, 0x2000
	s_nop 0
	global_load_lds_dwordx4 v[222:223], off
	v_lshl_add_u64 v[222:223], s[38:39], 0, v[128:129]
	s_mov_b32 m0, s33
	s_nop 0
	global_load_lds_dwordx4 v[222:223], off
	s_mov_b32 m0, s40
	s_nop 0
	global_load_lds_dwordx4 v[224:225], off
	s_waitcnt vmcnt(8)
	s_waitcnt lgkmcnt(0)
	s_barrier
	s_setprio 1
	s_waitcnt lgkmcnt(0)
	s_nop 0
	v_mfma_f32_16x16x32_bf16 v[60:63], v[144:147], v[184:187], v[60:63]
	v_mfma_f32_16x16x32_bf16 v[56:59], v[160:163], v[184:187], v[56:59]
	v_mfma_f32_16x16x32_bf16 v[44:47], v[144:147], v[192:195], v[44:47]
	v_mfma_f32_16x16x32_bf16 v[40:43], v[160:163], v[192:195], v[40:43]
	v_mfma_f32_16x16x32_bf16 v[28:31], v[144:147], v[200:203], v[28:31]
	v_mfma_f32_16x16x32_bf16 v[24:27], v[160:163], v[200:203], v[24:27]
	v_mfma_f32_16x16x32_bf16 v[12:15], v[144:147], v[208:211], v[12:15]
	v_mfma_f32_16x16x32_bf16 v[8:11], v[160:163], v[208:211], v[8:11]
	v_mfma_f32_16x16x32_bf16 v[60:63], v[156:159], v[188:191], v[60:63]
	v_mfma_f32_16x16x32_bf16 v[56:59], v[164:167], v[188:191], v[56:59]
	v_mfma_f32_16x16x32_bf16 v[44:47], v[156:159], v[196:199], v[44:47]
	v_mfma_f32_16x16x32_bf16 v[40:43], v[164:167], v[196:199], v[40:43]
	v_mfma_f32_16x16x32_bf16 v[28:31], v[156:159], v[204:207], v[28:31]
	v_mfma_f32_16x16x32_bf16 v[24:27], v[164:167], v[204:207], v[24:27]
	v_mfma_f32_16x16x32_bf16 v[12:15], v[156:159], v[212:215], v[12:15]
	v_mfma_f32_16x16x32_bf16 v[8:11], v[164:167], v[212:215], v[8:11]
	s_setprio 0
	s_setprio 1
	v_mfma_f32_16x16x32_bf16 v[52:55], v[168:171], v[184:187], v[52:55]
	v_mfma_f32_16x16x32_bf16 v[48:51], v[176:179], v[184:187], v[48:51]
	v_mfma_f32_16x16x32_bf16 v[36:39], v[168:171], v[192:195], v[36:39]
	v_mfma_f32_16x16x32_bf16 v[32:35], v[176:179], v[192:195], v[32:35]
	v_mfma_f32_16x16x32_bf16 v[20:23], v[168:171], v[200:203], v[20:23]
	v_mfma_f32_16x16x32_bf16 v[16:19], v[176:179], v[200:203], v[16:19]
	v_mfma_f32_16x16x32_bf16 v[4:7], v[168:171], v[208:211], v[4:7]
	v_mfma_f32_16x16x32_bf16 v[0:3], v[176:179], v[208:211], v[0:3]
	v_mfma_f32_16x16x32_bf16 v[52:55], v[172:175], v[188:191], v[52:55]
	v_mfma_f32_16x16x32_bf16 v[48:51], v[180:183], v[188:191], v[48:51]
	v_mfma_f32_16x16x32_bf16 v[36:39], v[172:175], v[196:199], v[36:39]
	v_mfma_f32_16x16x32_bf16 v[32:35], v[180:183], v[196:199], v[32:35]
	v_mfma_f32_16x16x32_bf16 v[20:23], v[172:175], v[204:207], v[20:23]
	v_mfma_f32_16x16x32_bf16 v[16:19], v[180:183], v[204:207], v[16:19]
	v_mfma_f32_16x16x32_bf16 v[4:7], v[172:175], v[212:215], v[4:7]
	v_mfma_f32_16x16x32_bf16 v[0:3], v[180:183], v[212:215], v[0:3]
	s_setprio 0
	s_barrier
	s_add_i32 s56, 0, 0x18000
	v_add_u32_e32 v155, s56, v149
	s_add_i32 s57, 0, 0x1c000
	ds_read_b128 v[144:147], v155
	ds_read_b128 v[156:159], v155 offset:1024
	ds_read_b128 v[160:163], v155 offset:2048
	ds_read_b128 v[164:167], v155 offset:3072
	v_add_u32_e32 v155, s57, v149
	ds_read_b128 v[168:171], v155
	ds_read_b128 v[172:175], v155 offset:1024
	ds_read_b128 v[176:179], v155 offset:2048
	ds_read_b128 v[180:183], v155 offset:3072
	s_add_u32 s38, s38, 0x2000
	s_addc_u32 s39, s39, 0
	s_mov_b32 m0, s41
	v_lshl_add_u64 v[226:227], s[38:39], 0, v[128:129]
	ds_read_b128 v[184:187], v153 offset:32768
	ds_read_b128 v[188:191], v153 offset:33792
	ds_read_b128 v[192:195], v153 offset:34816
	ds_read_b128 v[196:199], v153 offset:35840
	ds_read_b128 v[200:203], v153 offset:36864
	ds_read_b128 v[204:207], v153 offset:37888
	ds_read_b128 v[208:211], v153 offset:38912
	ds_read_b128 v[212:215], v153 offset:39936
	global_load_lds_dwordx4 v[226:227], off
	v_lshl_add_u64 v[226:227], s[38:39], 0, v[132:133]
	s_mov_b32 m0, s42
	s_nop 0
	global_load_lds_dwordx4 v[226:227], off
	s_waitcnt vmcnt(8)
	s_waitcnt lgkmcnt(0)
	s_barrier
	s_setprio 1
	s_waitcnt lgkmcnt(0)
	s_nop 0
	v_mfma_f32_16x16x32_bf16 v[124:127], v[144:147], v[184:187], v[124:127]
	v_mfma_f32_16x16x32_bf16 v[120:123], v[160:163], v[184:187], v[120:123]
	v_mfma_f32_16x16x32_bf16 v[108:111], v[144:147], v[192:195], v[108:111]
	v_mfma_f32_16x16x32_bf16 v[104:107], v[160:163], v[192:195], v[104:107]
	v_mfma_f32_16x16x32_bf16 v[92:95], v[144:147], v[200:203], v[92:95]
	v_mfma_f32_16x16x32_bf16 v[88:91], v[160:163], v[200:203], v[88:91]
	v_mfma_f32_16x16x32_bf16 v[76:79], v[144:147], v[208:211], v[76:79]
	v_mfma_f32_16x16x32_bf16 v[72:75], v[160:163], v[208:211], v[72:75]
	v_mfma_f32_16x16x32_bf16 v[124:127], v[156:159], v[188:191], v[124:127]
	v_mfma_f32_16x16x32_bf16 v[120:123], v[164:167], v[188:191], v[120:123]
	v_mfma_f32_16x16x32_bf16 v[108:111], v[156:159], v[196:199], v[108:111]
	v_mfma_f32_16x16x32_bf16 v[104:107], v[164:167], v[196:199], v[104:107]
	v_mfma_f32_16x16x32_bf16 v[92:95], v[156:159], v[204:207], v[92:95]
	v_mfma_f32_16x16x32_bf16 v[88:91], v[164:167], v[204:207], v[88:91]
	v_mfma_f32_16x16x32_bf16 v[76:79], v[156:159], v[212:215], v[76:79]
	v_mfma_f32_16x16x32_bf16 v[72:75], v[164:167], v[212:215], v[72:75]
	s_setprio 0
	s_setprio 1
	v_mfma_f32_16x16x32_bf16 v[116:119], v[168:171], v[184:187], v[116:119]
	v_mfma_f32_16x16x32_bf16 v[112:115], v[176:179], v[184:187], v[112:115]
	v_mfma_f32_16x16x32_bf16 v[100:103], v[168:171], v[192:195], v[100:103]
	v_mfma_f32_16x16x32_bf16 v[96:99], v[176:179], v[192:195], v[96:99]
	v_mfma_f32_16x16x32_bf16 v[84:87], v[168:171], v[200:203], v[84:87]
	v_mfma_f32_16x16x32_bf16 v[80:83], v[176:179], v[200:203], v[80:83]
	v_mfma_f32_16x16x32_bf16 v[68:71], v[168:171], v[208:211], v[68:71]
	v_mfma_f32_16x16x32_bf16 v[64:67], v[176:179], v[208:211], v[64:67]
	v_mfma_f32_16x16x32_bf16 v[116:119], v[172:175], v[188:191], v[116:119]
	v_mfma_f32_16x16x32_bf16 v[112:115], v[180:183], v[188:191], v[112:115]
	v_mfma_f32_16x16x32_bf16 v[100:103], v[172:175], v[196:199], v[100:103]
	v_mfma_f32_16x16x32_bf16 v[96:99], v[180:183], v[196:199], v[96:99]
	v_mfma_f32_16x16x32_bf16 v[84:87], v[172:175], v[204:207], v[84:87]
	v_mfma_f32_16x16x32_bf16 v[80:83], v[180:183], v[204:207], v[80:83]
	v_mfma_f32_16x16x32_bf16 v[68:71], v[172:175], v[212:215], v[68:71]
	v_mfma_f32_16x16x32_bf16 v[64:67], v[180:183], v[212:215], v[64:67]
	s_setprio 0
	s_barrier
	s_add_i32 s38, s56, s3
	v_lshl_add_u64 v[216:217], v[216:217], 0, s[18:19]
	s_mov_b32 m0, s38
	ds_read_b128 v[184:187], v153 offset:49152
	ds_read_b128 v[188:191], v153 offset:50176
	ds_read_b128 v[192:195], v153 offset:51200
	ds_read_b128 v[196:199], v153 offset:52224
	ds_read_b128 v[200:203], v153 offset:53248
	ds_read_b128 v[204:207], v153 offset:54272
	ds_read_b128 v[208:211], v153 offset:55296
	ds_read_b128 v[212:215], v153 offset:56320
	global_load_lds_dwordx4 v[216:217], off
	s_add_i32 m0, s38, 0x2000
	s_add_u32 s36, s36, 0x100080
	v_lshl_add_u64 v[216:217], v[218:219], 0, s[18:19]
	s_addc_u32 s37, s37, 0
	s_add_i32 s38, s57, s3
	global_load_lds_dwordx4 v[216:217], off
	v_lshl_add_u64 v[216:217], s[36:37], 0, v[130:131]
	s_mov_b32 m0, s38
	s_nop 0
	global_load_lds_dwordx4 v[216:217], off
	v_lshl_add_u64 v[216:217], s[36:37], 0, v[134:135]
	s_add_i32 m0, s38, 0x2000
	s_nop 0
	global_load_lds_dwordx4 v[216:217], off
	v_lshl_add_u64 v[216:217], v[222:223], 0, s[98:99]
	s_mov_b32 m0, s46
	s_nop 0
	global_load_lds_dwordx4 v[216:217], off
	v_lshl_add_u64 v[216:217], v[224:225], 0, s[98:99]
	s_mov_b32 m0, s47
	s_nop 0
	global_load_lds_dwordx4 v[216:217], off
	s_waitcnt vmcnt(8)
	s_waitcnt lgkmcnt(0)
	s_barrier
	s_setprio 1
	s_waitcnt lgkmcnt(0)
	v_mfma_f32_16x16x32_bf16 v[60:63], v[144:147], v[184:187], v[60:63]
	v_mfma_f32_16x16x32_bf16 v[56:59], v[160:163], v[184:187], v[56:59]
	v_mfma_f32_16x16x32_bf16 v[44:47], v[144:147], v[192:195], v[44:47]
	v_mfma_f32_16x16x32_bf16 v[40:43], v[160:163], v[192:195], v[40:43]
	v_mfma_f32_16x16x32_bf16 v[28:31], v[144:147], v[200:203], v[28:31]
	v_mfma_f32_16x16x32_bf16 v[24:27], v[160:163], v[200:203], v[24:27]
	v_mfma_f32_16x16x32_bf16 v[12:15], v[144:147], v[208:211], v[12:15]
	v_mfma_f32_16x16x32_bf16 v[8:11], v[160:163], v[208:211], v[8:11]
	v_mfma_f32_16x16x32_bf16 v[60:63], v[156:159], v[188:191], v[60:63]
	v_mfma_f32_16x16x32_bf16 v[56:59], v[164:167], v[188:191], v[56:59]
	v_mfma_f32_16x16x32_bf16 v[44:47], v[156:159], v[196:199], v[44:47]
	v_mfma_f32_16x16x32_bf16 v[40:43], v[164:167], v[196:199], v[40:43]
	v_mfma_f32_16x16x32_bf16 v[28:31], v[156:159], v[204:207], v[28:31]
	v_mfma_f32_16x16x32_bf16 v[24:27], v[164:167], v[204:207], v[24:27]
	v_mfma_f32_16x16x32_bf16 v[12:15], v[156:159], v[212:215], v[12:15]
	v_mfma_f32_16x16x32_bf16 v[8:11], v[164:167], v[212:215], v[8:11]
	s_setprio 0
	s_setprio 1
	v_mfma_f32_16x16x32_bf16 v[52:55], v[168:171], v[184:187], v[52:55]
	v_mfma_f32_16x16x32_bf16 v[48:51], v[176:179], v[184:187], v[48:51]
	v_mfma_f32_16x16x32_bf16 v[36:39], v[168:171], v[192:195], v[36:39]
	v_mfma_f32_16x16x32_bf16 v[32:35], v[176:179], v[192:195], v[32:35]
	v_mfma_f32_16x16x32_bf16 v[20:23], v[168:171], v[200:203], v[20:23]
	v_mfma_f32_16x16x32_bf16 v[16:19], v[176:179], v[200:203], v[16:19]
	v_mfma_f32_16x16x32_bf16 v[4:7], v[168:171], v[208:211], v[4:7]
	v_mfma_f32_16x16x32_bf16 v[0:3], v[176:179], v[208:211], v[0:3]
	v_mfma_f32_16x16x32_bf16 v[52:55], v[172:175], v[188:191], v[52:55]
	v_mfma_f32_16x16x32_bf16 v[48:51], v[180:183], v[188:191], v[48:51]
	v_mfma_f32_16x16x32_bf16 v[36:39], v[172:175], v[196:199], v[36:39]
	v_mfma_f32_16x16x32_bf16 v[32:35], v[180:183], v[196:199], v[32:35]
	v_mfma_f32_16x16x32_bf16 v[20:23], v[172:175], v[204:207], v[20:23]
	v_mfma_f32_16x16x32_bf16 v[16:19], v[180:183], v[204:207], v[16:19]
	v_mfma_f32_16x16x32_bf16 v[4:7], v[172:175], v[212:215], v[4:7]
	v_mfma_f32_16x16x32_bf16 v[0:3], v[180:183], v[212:215], v[0:3]
	s_setprio 0
	s_barrier
	s_add_i32 s55, s55, 2
	s_add_u32 s34, s34, 0x800000
	s_addc_u32 s35, s35, 0
	s_add_u32 s53, s53, 0x100
	s_addc_u32 s54, s54, 0
	s_cmp_gt_u32 s55, 61
	s_cbranch_scc0 .LBB0_954
	s_and_b64 vcc, exec, s[20:21]
	s_cbranch_vccz .LBB0_957
	s_barrier
